# streamed GEMM phases (in_proj, ffn_in, ffn_out): next unit's scalar set-up runs behind the epilogue's last store / accumulator clears, ahead of the wait and the half-workgroup barrier; loop re-entered
# baseline (speedup 1.0000x reference)
; #define STAGE(P_, BASE, br, kt) do { const u16* _gb = (BASE) + (long)(br) * K + (long)(kt) * BK; \
;     _Pragma("unroll") for (int _i = 0; _i < 2; ++_i) { \
;       __builtin_amdgcn_global_load_lds((const unsigned*)(_gb + (long)_i * 64 * K + lane_off), \
;         (unsigned*)((char*)(P_) + lds_wbase + _i * 8192), 16, 0, 0); } } while (0)
; #define LDA(dst, b, h) _Pragma("unroll") for (int m = 0; m < 4; ++m) _Pragma("unroll") for (int k = 0; k < 2; ++k) \
;     dst[m][k] = *reinterpret_cast<const bf16x8*>((char*)SA(b, h) + lds_byte(wr * 64 + m * 16 + fr, k * 32 + fq * 8))
; #define LDB(dst, b, h) _Pragma("unroll") for (int n = 0; n < 2; ++n) _Pragma("unroll") for (int k = 0; k < 2; ++k) \
;     dst[n][k] = *reinterpret_cast<const bf16x8*>((char*)SB(b, h) + lds_byte(wc * 32 + n * 16 + fr, k * 32 + fq * 8))
; #define MMA(ai, bj, At_, Bt_) do { __builtin_amdgcn_s_setprio(1); \
;     _Pragma("unroll") for (int m = 0; m < 4; ++m) _Pragma("unroll") for (int n = 0; n < 2; ++n) _Pragma("unroll") for (int k = 0; k < 2; ++k) \
;       acc[ai][bj][m][n] = __builtin_amdgcn_mfma_f32_16x16x32_bf16(At_[m][k], Bt_[n][k], acc[ai][bj][m][n], 0, 0, 0); \
;     __builtin_amdgcn_s_setprio(0); } while (0)
; #define WAIT_V(n) asm volatile("s_waitcnt vmcnt(" #n ")" ::: "memory")
; #define BAR __builtin_amdgcn_s_barrier()
; template <int PRE> ...
;     ...
;   for (int t = 0; t < nt; t += 2) {
;     LDB(B0, 0, 0); SCHED; LDA(At, 0, 0); STAGE(SA(1, 1), A, brow + HALF, t + 1);
;     WAIT_L(8); BAR; WAIT_L(0); MMA(0, 0, At, B0); BAR; SCHED;
;     LDB(B1, 0, 1); STAGEW(SB(0, 0), Bt, bcol, bcol_n, t + 2);
;     BAR; WAIT_L(0); MMA(0, 1, At, B1); BAR;
;     LDA(At, 0, 1); STAGEW(SA(0, 0), A, brow, brow_n, t + 2);
;     BAR; WAIT_L(0); MMA(1, 0, At, B0); BAR; SCHED;
;     STAGEW(SB(0, 1), Bt, bcol + HALF, bcol_n + HALF, t + 2);
;     WAIT_V(6); BAR; MMA(1, 1, At, B1); BAR;
;     LDB(B0, 1, 0); SCHED; LDA(At, 1, 0); STAGEW(SA(0, 1), A, brow + HALF, brow_n + HALF, t + 2);
;     WAIT_L(8); BAR; WAIT_L(0); MMA(0, 0, At, B0); BAR; SCHED;
;     LDB(B1, 1, 1); STAGEW(SB(1, 0), Bt, bcol, bcol_n, t + 3);
;     BAR; WAIT_L(0); MMA(0, 1, At, B1); BAR;
;     LDA(At, 1, 1); STAGEW(SA(1, 0), A, brow, brow_n, t + 3);
;     BAR; WAIT_L(0); MMA(1, 0, At, B0); BAR; SCHED;
;     STAGEW(SB(1, 1), Bt, bcol + HALF, bcol_n + HALF, t + 3);
;     WAIT_V(6); BAR; MMA(1, 1, At, B1); BAR;
;   }
.Lhm177_k:
.LBB0_181:
	v_add_u32_e32 v149, s81, v141
	ds_read_b128 v[136:139], v149
	ds_read_b128 v[150:153], v149 offset:1024
	ds_read_b128 v[154:157], v149 offset:2048
	ds_read_b128 v[158:161], v149 offset:3072
	s_add_i32 m0, s12, 0xc000
	ds_read_b128 v[168:171], v142
	ds_read_b128 v[172:175], v142 offset:1024
	ds_read_b128 v[176:179], v143
	ds_read_b128 v[180:183], v143 offset:1024
	ds_read_b128 v[184:187], v144
	ds_read_b128 v[188:191], v144 offset:1024
	ds_read_b128 v[192:195], v146
	ds_read_b128 v[210:213], v146 offset:1024
	global_load_lds_dwordx4 v[134:135], off
	v_lshl_add_u64 v[162:163], v[134:135], 0, s[86:87]
	s_add_i32 m0, s12, 0xe000
	s_nop 0
	global_load_lds_dwordx4 v[162:163], off
	s_waitcnt lgkmcnt(8)
	s_barrier
	s_waitcnt lgkmcnt(0)
	v_mfma_f32_16x16x32_bf16 v[126:129], v[168:171], v[136:139], v[126:129]
	v_mfma_f32_16x16x32_bf16 v[122:125], v[168:171], v[154:157], v[122:125]
	v_mfma_f32_16x16x32_bf16 v[118:121], v[176:179], v[136:139], v[118:121]
	v_mfma_f32_16x16x32_bf16 v[114:117], v[176:179], v[154:157], v[114:117]
	v_mfma_f32_16x16x32_bf16 v[110:113], v[184:187], v[136:139], v[110:113]
	v_mfma_f32_16x16x32_bf16 v[106:109], v[184:187], v[154:157], v[106:109]
	v_mfma_f32_16x16x32_bf16 v[102:105], v[192:195], v[136:139], v[102:105]
	v_mfma_f32_16x16x32_bf16 v[98:101], v[192:195], v[154:157], v[98:101]
	v_mfma_f32_16x16x32_bf16 v[126:129], v[172:175], v[150:153], v[126:129]
	v_mfma_f32_16x16x32_bf16 v[122:125], v[172:175], v[158:161], v[122:125]
	v_mfma_f32_16x16x32_bf16 v[118:121], v[180:183], v[150:153], v[118:121]
	v_mfma_f32_16x16x32_bf16 v[114:117], v[180:183], v[158:161], v[114:117]
	v_mfma_f32_16x16x32_bf16 v[110:113], v[188:191], v[150:153], v[110:113]
	v_mfma_f32_16x16x32_bf16 v[106:109], v[188:191], v[158:161], v[106:109]
	v_mfma_f32_16x16x32_bf16 v[102:105], v[210:213], v[150:153], v[102:105]
	v_mfma_f32_16x16x32_bf16 v[98:101], v[210:213], v[158:161], v[98:101]
	s_barrier
	s_add_i32 s1, s38, 2
	s_cmp_lt_u32 s38, 30
	s_cselect_b64 s[2:3], -1, 0
	s_and_b64 vcc, s[2:3], exec
	s_cselect_b32 s6, s10, s11
	s_cselect_b32 s3, 0, 0xffffffe0
	s_cselect_b32 s40, s0, s31
	s_cselect_b32 s42, s36, s35
	s_cselect_b32 s2, s34, s37
	s_ashr_i32 s7, s6, 31
	s_lshl_b64 s[6:7], s[6:7], 12
	s_add_u32 s39, s52, s6
	s_addc_u32 s41, s53, s7
	s_add_i32 s18, s1, s3
	s_lshl_b64 s[6:7], s[18:19], 7
	s_add_u32 s44, s39, s6
	s_addc_u32 s45, s41, s7
	s_mov_b32 m0, s13
	v_add_u32_e32 v149, s82, v141
	v_lshl_add_u64 v[162:163], s[44:45], 0, v[130:131]
	ds_read_b128 v[214:217], v149
	ds_read_b128 v[218:221], v149 offset:1024
	ds_read_b128 v[222:225], v149 offset:2048
	ds_read_b128 v[226:229], v149 offset:3072
	global_load_lds_dwordx4 v[162:163], off
	v_lshl_add_u64 v[162:163], v[162:163], 0, s[86:87]
	s_mov_b32 m0, s14
	s_nop 0
	global_load_lds_dwordx4 v[162:163], off
	s_barrier
	s_waitcnt lgkmcnt(0)
	v_mfma_f32_16x16x32_bf16 v[94:97], v[168:171], v[214:217], v[94:97]
	v_mfma_f32_16x16x32_bf16 v[90:93], v[168:171], v[222:225], v[90:93]
	v_mfma_f32_16x16x32_bf16 v[86:89], v[176:179], v[214:217], v[86:89]
	v_mfma_f32_16x16x32_bf16 v[82:85], v[176:179], v[222:225], v[82:85]
	v_mfma_f32_16x16x32_bf16 v[78:81], v[184:187], v[214:217], v[78:81]
	v_mfma_f32_16x16x32_bf16 v[74:77], v[184:187], v[222:225], v[74:77]
	v_mfma_f32_16x16x32_bf16 v[70:73], v[192:195], v[214:217], v[70:73]
	v_mfma_f32_16x16x32_bf16 v[64:67], v[192:195], v[222:225], v[64:67]
	v_mfma_f32_16x16x32_bf16 v[94:97], v[172:175], v[218:221], v[94:97]
	v_mfma_f32_16x16x32_bf16 v[90:93], v[172:175], v[226:229], v[90:93]
	v_mfma_f32_16x16x32_bf16 v[86:89], v[180:183], v[218:221], v[86:89]
	v_mfma_f32_16x16x32_bf16 v[82:85], v[180:183], v[226:229], v[82:85]
	v_mfma_f32_16x16x32_bf16 v[78:81], v[188:191], v[218:221], v[78:81]
	v_mfma_f32_16x16x32_bf16 v[74:77], v[188:191], v[226:229], v[74:77]
	v_mfma_f32_16x16x32_bf16 v[70:73], v[210:213], v[218:221], v[70:73]
	v_mfma_f32_16x16x32_bf16 v[64:67], v[210:213], v[226:229], v[64:67]
	s_ashr_i32 s41, s40, 31
	s_lshl_b64 s[40:41], s[40:41], 12
	s_add_u32 s3, s50, s40
	s_addc_u32 s18, s51, s41
	s_add_u32 s40, s3, s6
	s_addc_u32 s41, s18, s7
	s_mov_b32 m0, s12
	v_lshl_add_u64 v[162:163], s[40:41], 0, v[130:131]
	s_barrier
	ds_read_b128 v[168:171], v142 offset:16384
	ds_read_b128 v[172:175], v142 offset:17408
	ds_read_b128 v[176:179], v143 offset:16384
	ds_read_b128 v[180:183], v143 offset:17408
	ds_read_b128 v[184:187], v144 offset:16384
	ds_read_b128 v[188:191], v144 offset:17408
	ds_read_b128 v[192:195], v146 offset:16384
	ds_read_b128 v[210:213], v146 offset:17408
	global_load_lds_dwordx4 v[162:163], off
	v_lshl_add_u64 v[162:163], v[162:163], 0, s[86:87]
	s_mov_b32 m0, s15
	s_nop 0
	global_load_lds_dwordx4 v[162:163], off
	s_barrier
	s_waitcnt lgkmcnt(0)
	v_mfma_f32_16x16x32_bf16 v[60:63], v[168:171], v[136:139], v[60:63]
	v_mfma_f32_16x16x32_bf16 v[56:59], v[168:171], v[154:157], v[56:59]
	v_mfma_f32_16x16x32_bf16 v[52:55], v[176:179], v[136:139], v[52:55]
	v_mfma_f32_16x16x32_bf16 v[48:51], v[176:179], v[154:157], v[48:51]
	v_mfma_f32_16x16x32_bf16 v[44:47], v[184:187], v[136:139], v[44:47]
	v_mfma_f32_16x16x32_bf16 v[40:43], v[184:187], v[154:157], v[40:43]
	v_mfma_f32_16x16x32_bf16 v[36:39], v[192:195], v[136:139], v[36:39]
	v_mfma_f32_16x16x32_bf16 v[32:35], v[192:195], v[154:157], v[32:35]
	v_mfma_f32_16x16x32_bf16 v[60:63], v[172:175], v[150:153], v[60:63]
	v_mfma_f32_16x16x32_bf16 v[56:59], v[172:175], v[158:161], v[56:59]
	v_mfma_f32_16x16x32_bf16 v[52:55], v[180:183], v[150:153], v[52:55]
	v_mfma_f32_16x16x32_bf16 v[48:51], v[180:183], v[158:161], v[48:51]
	v_mfma_f32_16x16x32_bf16 v[44:47], v[188:191], v[150:153], v[44:47]
	v_mfma_f32_16x16x32_bf16 v[40:43], v[188:191], v[158:161], v[40:43]
	v_mfma_f32_16x16x32_bf16 v[36:39], v[210:213], v[150:153], v[36:39]
	v_mfma_f32_16x16x32_bf16 v[32:35], v[210:213], v[158:161], v[32:35]
	s_barrier
; #define STAGE(P_, BASE, br, kt) do { const u16* _gb = (BASE) + (long)(br) * K + (long)(kt) * BK; \
;     _Pragma("unroll") for (int _i = 0; _i < 2; ++_i) { \
;       __builtin_amdgcn_global_load_lds((const unsigned*)(_gb + (long)_i * 64 * K + lane_off), \
;         (unsigned*)((char*)(P_) + lds_wbase + _i * 8192), 16, 0, 0); } } while (0)
; #define LDA(dst, b, h) _Pragma("unroll") for (int m = 0; m < 4; ++m) _Pragma("unroll") for (int k = 0; k < 2; ++k) \
;     dst[m][k] = *reinterpret_cast<const bf16x8*>((char*)SA(b, h) + lds_byte(wr * 64 + m * 16 + fr, k * 32 + fq * 8))
; #define LDB(dst, b, h) _Pragma("unroll") for (int n = 0; n < 2; ++n) _Pragma("unroll") for (int k = 0; k < 2; ++k) \
;     dst[n][k] = *reinterpret_cast<const bf16x8*>((char*)SB(b, h) + lds_byte(wc * 32 + n * 16 + fr, k * 32 + fq * 8))
; #define MMA(ai, bj, At_, Bt_) do { __builtin_amdgcn_s_setprio(1); \
;     _Pragma("unroll") for (int m = 0; m < 4; ++m) _Pragma("unroll") for (int n = 0; n < 2; ++n) _Pragma("unroll") for (int k = 0; k < 2; ++k) \
;       acc[ai][bj][m][n] = __builtin_amdgcn_mfma_f32_16x16x32_bf16(At_[m][k], Bt_[n][k], acc[ai][bj][m][n], 0, 0, 0); \
;     __builtin_amdgcn_s_setprio(0); } while (0)
; #define WAIT_V(n) asm volatile("s_waitcnt vmcnt(" #n ")" ::: "memory")
; #define BAR __builtin_amdgcn_s_barrier()
; template <int PRE> ...
;     ...
;   for (int t = 0; t < nt; t += 2) {
;     LDB(B0, 0, 0); SCHED; LDA(At, 0, 0); STAGE(SA(1, 1), A, brow + HALF, t + 1);
;     WAIT_L(8); BAR; WAIT_L(0); MMA(0, 0, At, B0); BAR; SCHED;
;     LDB(B1, 0, 1); STAGEW(SB(0, 0), Bt, bcol, bcol_n, t + 2);
;     BAR; WAIT_L(0); MMA(0, 1, At, B1); BAR;
;     LDA(At, 0, 1); STAGEW(SA(0, 0), A, brow, brow_n, t + 2);
;     BAR; WAIT_L(0); MMA(1, 0, At, B0); BAR; SCHED;
;     STAGEW(SB(0, 1), Bt, bcol + HALF, bcol_n + HALF, t + 2);
;     WAIT_V(6); BAR; MMA(1, 1, At, B1); BAR;
;     LDB(B0, 1, 0); SCHED; LDA(At, 1, 0); STAGEW(SA(0, 1), A, brow + HALF, brow_n + HALF, t + 2);
;     WAIT_L(8); BAR; WAIT_L(0); MMA(0, 0, At, B0); BAR; SCHED;
;     LDB(B1, 1, 1); STAGEW(SB(1, 0), Bt, bcol, bcol_n, t + 3);
;     BAR; WAIT_L(0); MMA(0, 1, At, B1); BAR;
;     LDA(At, 1, 1); STAGEW(SA(1, 0), A, brow, brow_n, t + 3);
;     BAR; WAIT_L(0); MMA(1, 0, At, B0); BAR; SCHED;
;     STAGEW(SB(1, 1), Bt, bcol + HALF, bcol_n + HALF, t + 3);
;     WAIT_V(6); BAR; MMA(1, 1, At, B1); BAR;
;   }
	s_ashr_i32 s43, s42, 31
	s_lshl_b64 s[40:41], s[42:43], 12
	s_add_u32 s3, s52, s40
	s_addc_u32 s18, s53, s41
	s_add_u32 s40, s3, s6
	s_addc_u32 s41, s18, s7
	s_mov_b32 m0, s16
	v_lshl_add_u64 v[136:137], s[40:41], 0, v[130:131]
	global_load_lds_dwordx4 v[136:137], off
	v_lshl_add_u64 v[136:137], v[136:137], 0, s[86:87]
	s_mov_b32 m0, s17
	s_nop 0
	global_load_lds_dwordx4 v[136:137], off
	s_waitcnt vmcnt(6)
	s_barrier
	v_mfma_f32_16x16x32_bf16 v[28:31], v[168:171], v[214:217], v[28:31]
	v_mfma_f32_16x16x32_bf16 v[24:27], v[168:171], v[222:225], v[24:27]
	v_mfma_f32_16x16x32_bf16 v[20:23], v[176:179], v[214:217], v[20:23]
	v_mfma_f32_16x16x32_bf16 v[16:19], v[176:179], v[222:225], v[16:19]
	v_mfma_f32_16x16x32_bf16 v[12:15], v[184:187], v[214:217], v[12:15]
	v_mfma_f32_16x16x32_bf16 v[8:11], v[184:187], v[222:225], v[8:11]
	v_mfma_f32_16x16x32_bf16 v[4:7], v[192:195], v[214:217], v[4:7]
	v_mfma_f32_16x16x32_bf16 v[0:3], v[192:195], v[222:225], v[0:3]
	v_mfma_f32_16x16x32_bf16 v[28:31], v[172:175], v[218:221], v[28:31]
	v_mfma_f32_16x16x32_bf16 v[24:27], v[172:175], v[226:229], v[24:27]
	v_mfma_f32_16x16x32_bf16 v[20:23], v[180:183], v[218:221], v[20:23]
	v_mfma_f32_16x16x32_bf16 v[16:19], v[180:183], v[226:229], v[16:19]
	v_mfma_f32_16x16x32_bf16 v[12:15], v[188:191], v[218:221], v[12:15]
	v_mfma_f32_16x16x32_bf16 v[8:11], v[188:191], v[226:229], v[8:11]
	v_mfma_f32_16x16x32_bf16 v[4:7], v[210:213], v[218:221], v[4:7]
	v_mfma_f32_16x16x32_bf16 v[0:3], v[210:213], v[226:229], v[0:3]
	v_add_u32_e32 v149, s83, v141
	s_barrier
	ds_read_b128 v[136:139], v149
	ds_read_b128 v[150:153], v149 offset:1024
	ds_read_b128 v[154:157], v149 offset:2048
	ds_read_b128 v[158:161], v149 offset:3072
	s_ashr_i32 s3, s2, 31
	s_lshl_b64 s[2:3], s[2:3], 12
	s_add_u32 s2, s50, s2
	s_addc_u32 s3, s51, s3
	s_add_u32 s2, s2, s6
	s_addc_u32 s3, s3, s7
	s_mov_b32 m0, s21
	v_lshl_add_u64 v[162:163], s[2:3], 0, v[130:131]
	ds_read_b128 v[168:171], v142 offset:32768
	ds_read_b128 v[172:175], v142 offset:33792
	ds_read_b128 v[176:179], v143 offset:32768
	ds_read_b128 v[180:183], v143 offset:33792
	ds_read_b128 v[184:187], v144 offset:32768
	ds_read_b128 v[188:191], v144 offset:33792
	ds_read_b128 v[192:195], v146 offset:32768
	ds_read_b128 v[210:213], v146 offset:33792
	global_load_lds_dwordx4 v[162:163], off
	v_lshl_add_u64 v[162:163], v[162:163], 0, s[86:87]
	s_mov_b32 m0, s22
	s_nop 0
	global_load_lds_dwordx4 v[162:163], off
	s_waitcnt lgkmcnt(8)
	s_barrier
	s_waitcnt lgkmcnt(0)
	v_mfma_f32_16x16x32_bf16 v[126:129], v[168:171], v[136:139], v[126:129]
	v_mfma_f32_16x16x32_bf16 v[122:125], v[168:171], v[154:157], v[122:125]
	v_mfma_f32_16x16x32_bf16 v[118:121], v[176:179], v[136:139], v[118:121]
	v_mfma_f32_16x16x32_bf16 v[114:117], v[176:179], v[154:157], v[114:117]
	v_mfma_f32_16x16x32_bf16 v[110:113], v[184:187], v[136:139], v[110:113]
	v_mfma_f32_16x16x32_bf16 v[106:109], v[184:187], v[154:157], v[106:109]
	v_mfma_f32_16x16x32_bf16 v[102:105], v[192:195], v[136:139], v[102:105]
	v_mfma_f32_16x16x32_bf16 v[98:101], v[192:195], v[154:157], v[98:101]
	v_mfma_f32_16x16x32_bf16 v[126:129], v[172:175], v[150:153], v[126:129]
	v_mfma_f32_16x16x32_bf16 v[122:125], v[172:175], v[158:161], v[122:125]
	v_mfma_f32_16x16x32_bf16 v[118:121], v[180:183], v[150:153], v[118:121]
	v_mfma_f32_16x16x32_bf16 v[114:117], v[180:183], v[158:161], v[114:117]
	v_mfma_f32_16x16x32_bf16 v[110:113], v[188:191], v[150:153], v[110:113]
	v_mfma_f32_16x16x32_bf16 v[106:109], v[188:191], v[158:161], v[106:109]
	v_mfma_f32_16x16x32_bf16 v[102:105], v[210:213], v[150:153], v[102:105]
	v_mfma_f32_16x16x32_bf16 v[98:101], v[210:213], v[158:161], v[98:101]
	s_barrier
	s_cmp_lt_u32 s38, 29
	s_cselect_b32 s2, s10, s11
	s_cselect_b32 s7, 0, 0xffffffe0
	s_cselect_b32 s6, s0, s31
	s_cselect_b32 s40, s36, s35
	s_ashr_i32 s3, s2, 31
	s_lshl_b64 s[2:3], s[2:3], 12
	s_add_u32 s39, s52, s2
	s_addc_u32 s41, s53, s3
	s_add_i32 s2, s7, s38
	s_add_i32 s18, s2, 3
	s_lshl_b64 s[2:3], s[18:19], 7
	s_add_u32 s38, s39, s2
	s_addc_u32 s39, s41, s3
	s_mov_b32 m0, s23
	v_add_u32_e32 v149, s84, v141
	v_lshl_add_u64 v[162:163], s[38:39], 0, v[130:131]
	ds_read_b128 v[214:217], v149
	ds_read_b128 v[218:221], v149 offset:1024
	ds_read_b128 v[222:225], v149 offset:2048
	ds_read_b128 v[226:229], v149 offset:3072
	global_load_lds_dwordx4 v[162:163], off
	v_lshl_add_u64 v[162:163], v[162:163], 0, s[86:87]
	s_mov_b32 m0, s24
	s_nop 0
	global_load_lds_dwordx4 v[162:163], off
	s_barrier
; #define STAGE(P_, BASE, br, kt) do { const u16* _gb = (BASE) + (long)(br) * K + (long)(kt) * BK; \
;     _Pragma("unroll") for (int _i = 0; _i < 2; ++_i) { \
;       __builtin_amdgcn_global_load_lds((const unsigned*)(_gb + (long)_i * 64 * K + lane_off), \
;         (unsigned*)((char*)(P_) + lds_wbase + _i * 8192), 16, 0, 0); } } while (0)
; #define LDA(dst, b, h) _Pragma("unroll") for (int m = 0; m < 4; ++m) _Pragma("unroll") for (int k = 0; k < 2; ++k) \
;     dst[m][k] = *reinterpret_cast<const bf16x8*>((char*)SA(b, h) + lds_byte(wr * 64 + m * 16 + fr, k * 32 + fq * 8))
; #define LDB(dst, b, h) _Pragma("unroll") for (int n = 0; n < 2; ++n) _Pragma("unroll") for (int k = 0; k < 2; ++k) \
;     dst[n][k] = *reinterpret_cast<const bf16x8*>((char*)SB(b, h) + lds_byte(wc * 32 + n * 16 + fr, k * 32 + fq * 8))
; #define MMA(ai, bj, At_, Bt_) do { __builtin_amdgcn_s_setprio(1); \
;     _Pragma("unroll") for (int m = 0; m < 4; ++m) _Pragma("unroll") for (int n = 0; n < 2; ++n) _Pragma("unroll") for (int k = 0; k < 2; ++k) \
;       acc[ai][bj][m][n] = __builtin_amdgcn_mfma_f32_16x16x32_bf16(At_[m][k], Bt_[n][k], acc[ai][bj][m][n], 0, 0, 0); \
;     __builtin_amdgcn_s_setprio(0); } while (0)
; #define WAIT_V(n) asm volatile("s_waitcnt vmcnt(" #n ")" ::: "memory")
; #define BAR __builtin_amdgcn_s_barrier()
; template <int PRE> ...
;     ...
;   for (int t = 0; t < nt; t += 2) {
;     LDB(B0, 0, 0); SCHED; LDA(At, 0, 0); STAGE(SA(1, 1), A, brow + HALF, t + 1);
;     WAIT_L(8); BAR; WAIT_L(0); MMA(0, 0, At, B0); BAR; SCHED;
;     LDB(B1, 0, 1); STAGEW(SB(0, 0), Bt, bcol, bcol_n, t + 2);
;     BAR; WAIT_L(0); MMA(0, 1, At, B1); BAR;
;     LDA(At, 0, 1); STAGEW(SA(0, 0), A, brow, brow_n, t + 2);
;     BAR; WAIT_L(0); MMA(1, 0, At, B0); BAR; SCHED;
;     STAGEW(SB(0, 1), Bt, bcol + HALF, bcol_n + HALF, t + 2);
;     WAIT_V(6); BAR; MMA(1, 1, At, B1); BAR;
;     LDB(B0, 1, 0); SCHED; LDA(At, 1, 0); STAGEW(SA(0, 1), A, brow + HALF, brow_n + HALF, t + 2);
;     WAIT_L(8); BAR; WAIT_L(0); MMA(0, 0, At, B0); BAR; SCHED;
;     LDB(B1, 1, 1); STAGEW(SB(1, 0), Bt, bcol, bcol_n, t + 3);
;     BAR; WAIT_L(0); MMA(0, 1, At, B1); BAR;
;     LDA(At, 1, 1); STAGEW(SA(1, 0), A, brow, brow_n, t + 3);
;     BAR; WAIT_L(0); MMA(1, 0, At, B0); BAR; SCHED;
;     STAGEW(SB(1, 1), Bt, bcol + HALF, bcol_n + HALF, t + 3);
;     WAIT_V(6); BAR; MMA(1, 1, At, B1); BAR;
;   }
;   if (wr == 0) BAR;
	s_waitcnt lgkmcnt(0)
	v_mfma_f32_16x16x32_bf16 v[94:97], v[168:171], v[214:217], v[94:97]
	v_mfma_f32_16x16x32_bf16 v[90:93], v[168:171], v[222:225], v[90:93]
	v_mfma_f32_16x16x32_bf16 v[86:89], v[176:179], v[214:217], v[86:89]
	v_mfma_f32_16x16x32_bf16 v[82:85], v[176:179], v[222:225], v[82:85]
	v_mfma_f32_16x16x32_bf16 v[78:81], v[184:187], v[214:217], v[78:81]
	v_mfma_f32_16x16x32_bf16 v[74:77], v[184:187], v[222:225], v[74:77]
	v_mfma_f32_16x16x32_bf16 v[70:73], v[192:195], v[214:217], v[70:73]
	v_mfma_f32_16x16x32_bf16 v[64:67], v[192:195], v[222:225], v[64:67]
	v_mfma_f32_16x16x32_bf16 v[94:97], v[172:175], v[218:221], v[94:97]
	v_mfma_f32_16x16x32_bf16 v[90:93], v[172:175], v[226:229], v[90:93]
	v_mfma_f32_16x16x32_bf16 v[86:89], v[180:183], v[218:221], v[86:89]
	v_mfma_f32_16x16x32_bf16 v[82:85], v[180:183], v[226:229], v[82:85]
	v_mfma_f32_16x16x32_bf16 v[78:81], v[188:191], v[218:221], v[78:81]
	v_mfma_f32_16x16x32_bf16 v[74:77], v[188:191], v[226:229], v[74:77]
	v_mfma_f32_16x16x32_bf16 v[70:73], v[210:213], v[218:221], v[70:73]
	v_mfma_f32_16x16x32_bf16 v[64:67], v[210:213], v[226:229], v[64:67]
	s_ashr_i32 s7, s6, 31
	s_lshl_b64 s[6:7], s[6:7], 12
	s_add_u32 s6, s50, s6
	s_addc_u32 s7, s51, s7
	s_add_u32 s6, s6, s2
	s_addc_u32 s7, s7, s3
	s_mov_b32 m0, s25
	v_lshl_add_u64 v[162:163], s[6:7], 0, v[130:131]
	s_barrier
	ds_read_b128 v[168:171], v142 offset:49152
	ds_read_b128 v[172:175], v142 offset:50176
	ds_read_b128 v[176:179], v143 offset:49152
	ds_read_b128 v[180:183], v143 offset:50176
	ds_read_b128 v[184:187], v144 offset:49152
	ds_read_b128 v[188:191], v144 offset:50176
	ds_read_b128 v[192:195], v146 offset:49152
	ds_read_b128 v[210:213], v146 offset:50176
	global_load_lds_dwordx4 v[162:163], off
	v_lshl_add_u64 v[162:163], v[162:163], 0, s[86:87]
	s_mov_b32 m0, s26
	s_nop 0
	global_load_lds_dwordx4 v[162:163], off
	s_barrier
	s_waitcnt lgkmcnt(0)
	v_mfma_f32_16x16x32_bf16 v[60:63], v[168:171], v[136:139], v[60:63]
	v_mfma_f32_16x16x32_bf16 v[56:59], v[168:171], v[154:157], v[56:59]
	v_mfma_f32_16x16x32_bf16 v[52:55], v[176:179], v[136:139], v[52:55]
	v_mfma_f32_16x16x32_bf16 v[48:51], v[176:179], v[154:157], v[48:51]
	v_mfma_f32_16x16x32_bf16 v[44:47], v[184:187], v[136:139], v[44:47]
	v_mfma_f32_16x16x32_bf16 v[40:43], v[184:187], v[154:157], v[40:43]
	v_mfma_f32_16x16x32_bf16 v[36:39], v[192:195], v[136:139], v[36:39]
	v_mfma_f32_16x16x32_bf16 v[32:35], v[192:195], v[154:157], v[32:35]
	v_mfma_f32_16x16x32_bf16 v[60:63], v[172:175], v[150:153], v[60:63]
	v_mfma_f32_16x16x32_bf16 v[56:59], v[172:175], v[158:161], v[56:59]
	v_mfma_f32_16x16x32_bf16 v[52:55], v[180:183], v[150:153], v[52:55]
	v_mfma_f32_16x16x32_bf16 v[48:51], v[180:183], v[158:161], v[48:51]
	v_mfma_f32_16x16x32_bf16 v[44:47], v[188:191], v[150:153], v[44:47]
	v_mfma_f32_16x16x32_bf16 v[40:43], v[188:191], v[158:161], v[40:43]
	v_mfma_f32_16x16x32_bf16 v[36:39], v[210:213], v[150:153], v[36:39]
	v_mfma_f32_16x16x32_bf16 v[32:35], v[210:213], v[158:161], v[32:35]
	s_barrier
	s_ashr_i32 s41, s40, 31
	s_lshl_b64 s[6:7], s[40:41], 12
	s_add_u32 s6, s52, s6
	s_addc_u32 s7, s53, s7
	s_add_u32 s2, s6, s2
	s_addc_u32 s3, s7, s3
	s_mov_b32 m0, s27
	v_lshl_add_u64 v[136:137], s[2:3], 0, v[130:131]
	global_load_lds_dwordx4 v[136:137], off
	v_lshl_add_u64 v[136:137], v[136:137], 0, s[86:87]
	s_mov_b32 m0, s28
	s_nop 0
	global_load_lds_dwordx4 v[136:137], off
	s_waitcnt vmcnt(6)
	s_barrier
	v_mfma_f32_16x16x32_bf16 v[28:31], v[168:171], v[214:217], v[28:31]
	v_mfma_f32_16x16x32_bf16 v[24:27], v[168:171], v[222:225], v[24:27]
	v_mfma_f32_16x16x32_bf16 v[20:23], v[176:179], v[214:217], v[20:23]
	v_mfma_f32_16x16x32_bf16 v[16:19], v[176:179], v[222:225], v[16:19]
	v_mfma_f32_16x16x32_bf16 v[12:15], v[184:187], v[214:217], v[12:15]
	v_mfma_f32_16x16x32_bf16 v[8:11], v[184:187], v[222:225], v[8:11]
	v_mfma_f32_16x16x32_bf16 v[4:7], v[192:195], v[214:217], v[4:7]
	v_mfma_f32_16x16x32_bf16 v[0:3], v[192:195], v[222:225], v[0:3]
	v_mfma_f32_16x16x32_bf16 v[28:31], v[172:175], v[218:221], v[28:31]
	v_mfma_f32_16x16x32_bf16 v[24:27], v[172:175], v[226:229], v[24:27]
	v_mfma_f32_16x16x32_bf16 v[20:23], v[180:183], v[218:221], v[20:23]
	v_mfma_f32_16x16x32_bf16 v[16:19], v[180:183], v[226:229], v[16:19]
	v_mfma_f32_16x16x32_bf16 v[12:15], v[188:191], v[218:221], v[12:15]
	v_mfma_f32_16x16x32_bf16 v[8:11], v[188:191], v[226:229], v[8:11]
	v_mfma_f32_16x16x32_bf16 v[4:7], v[210:213], v[218:221], v[4:7]
	v_mfma_f32_16x16x32_bf16 v[0:3], v[210:213], v[226:229], v[0:3]
	v_lshl_add_u64 v[134:135], v[134:135], 0, s[46:47]
	s_mov_b32 s38, s1
	s_barrier
	s_cbranch_vccnz .LBB0_181
	s_andn2_b64 vcc, exec, s[58:59]
	s_cbranch_vccnz .LBB0_184
	s_barrier

;     ...
;   for (int u = vb; u < nunits; u += ustride) {
;     const int tm = u % nM, tn = u / nM + ((tn_skip >= 0 && u / nM >= tn_skip) ? 1 : 0);
;     const int brow = tn * 256, bcol = tm * 256;
;     const int un = u + ustride;
;     const bool has_next = un < nunits;
;     const int tn_n = un / nM + ((tn_skip >= 0 && un / nM >= tn_skip) ? 1 : 0);
;     const int brow_n = has_next ? tn_n * 256 : brow, bcol_n = has_next ? (un % nM) * 256 : bcol;
; #pragma unroll
;     for (int a = 0; a < 2; ++a)
; #pragma unroll
;       for (int b = 0; b < 2; ++b)
; #pragma unroll
;         for (int m = 0; m < 4; ++m)
; #pragma unroll
;           for (int n = 0; n < 2; ++n) acc[a][b][m][n] = f32x4{0.f, 0.f, 0.f, 0.f};
;     gemm_kloop<3>(W, Act, K, brow, bcol, brow_n, bcol_n, acc, tid, wvi);
;     ...
;     asm volatile("s_waitcnt vmcnt(0)" ::: "memory");
;     if (has_next && wr == 1) __builtin_amdgcn_s_barrier();
.LBB0_268:
	s_nop 1
	v_mov_b32_e32 v0, 0
	v_mov_b32_e32 v1, v0
	v_mov_b32_e32 v2, v0
	v_mov_b32_e32 v3, v0
	v_mov_b32_e32 v4, v0
	v_mov_b32_e32 v5, v0
	v_mov_b32_e32 v6, v0
	v_mov_b32_e32 v7, v0
	v_mov_b32_e32 v8, v0
	v_mov_b32_e32 v9, v0
	v_mov_b32_e32 v10, v0
	v_mov_b32_e32 v11, v0
	v_mov_b32_e32 v12, v0
	v_mov_b32_e32 v13, v0
	v_mov_b32_e32 v14, v0
	v_mov_b32_e32 v15, v0
	v_mov_b32_e32 v16, v0
	v_mov_b32_e32 v17, v0
	v_mov_b32_e32 v18, v0
	v_mov_b32_e32 v19, v0
	v_mov_b32_e32 v20, v0
	v_mov_b32_e32 v21, v0
	v_mov_b32_e32 v22, v0
	v_mov_b32_e32 v23, v0
	v_mov_b32_e32 v24, v0
	v_mov_b32_e32 v25, v0
	v_mov_b32_e32 v26, v0
	v_mov_b32_e32 v27, v0
	v_mov_b32_e32 v28, v0
	v_mov_b32_e32 v29, v0
	v_mov_b32_e32 v30, v0
	v_mov_b32_e32 v31, v0
	v_mov_b32_e32 v32, v0
	v_mov_b32_e32 v33, v0
	v_mov_b32_e32 v34, v0
	v_mov_b32_e32 v35, v0
	v_mov_b32_e32 v36, v0
	v_mov_b32_e32 v37, v0
	v_mov_b32_e32 v38, v0
	v_mov_b32_e32 v39, v0
	v_mov_b32_e32 v40, v0
	v_mov_b32_e32 v41, v0
	v_mov_b32_e32 v42, v0
	v_mov_b32_e32 v43, v0
	v_mov_b32_e32 v44, v0
	v_mov_b32_e32 v45, v0
	v_mov_b32_e32 v46, v0
	v_mov_b32_e32 v47, v0
	v_mov_b32_e32 v48, v0
	v_mov_b32_e32 v49, v0
	v_mov_b32_e32 v50, v0
	v_mov_b32_e32 v51, v0
	v_mov_b32_e32 v52, v0
	v_mov_b32_e32 v53, v0
	v_mov_b32_e32 v54, v0
	v_mov_b32_e32 v55, v0
	v_mov_b32_e32 v56, v0
	v_mov_b32_e32 v57, v0
	v_mov_b32_e32 v58, v0
	v_mov_b32_e32 v59, v0
	v_mov_b32_e32 v60, v0
	v_mov_b32_e32 v61, v0
	v_mov_b32_e32 v62, v0
	v_mov_b32_e32 v63, v0
	v_mov_b32_e32 v64, v0
	v_mov_b32_e32 v65, v0
	v_mov_b32_e32 v66, v0
	v_mov_b32_e32 v67, v0
	v_mov_b32_e32 v70, v0
	v_mov_b32_e32 v71, v0
	v_mov_b32_e32 v72, v0
	v_mov_b32_e32 v73, v0
	v_mov_b32_e32 v74, v0
	v_mov_b32_e32 v75, v0
	v_mov_b32_e32 v76, v0
	v_mov_b32_e32 v77, v0
	v_mov_b32_e32 v78, v0
	v_mov_b32_e32 v79, v0
	v_mov_b32_e32 v80, v0
	v_mov_b32_e32 v81, v0
	v_mov_b32_e32 v82, v0
	v_mov_b32_e32 v83, v0
	v_mov_b32_e32 v84, v0
	v_mov_b32_e32 v85, v0
	v_mov_b32_e32 v86, v0
	v_mov_b32_e32 v87, v0
	v_mov_b32_e32 v88, v0
	v_mov_b32_e32 v89, v0
	v_mov_b32_e32 v90, v0
	v_mov_b32_e32 v91, v0
	v_mov_b32_e32 v92, v0
	v_mov_b32_e32 v93, v0
	v_mov_b32_e32 v94, v0
	v_mov_b32_e32 v95, v0
	v_mov_b32_e32 v96, v0
	v_mov_b32_e32 v97, v0
	v_mov_b32_e32 v98, v0
	v_mov_b32_e32 v99, v0
	v_mov_b32_e32 v100, v0
	v_mov_b32_e32 v101, v0
	v_mov_b32_e32 v102, v0
	v_mov_b32_e32 v103, v0
	v_mov_b32_e32 v104, v0
	v_mov_b32_e32 v105, v0
	v_mov_b32_e32 v106, v0
	v_mov_b32_e32 v107, v0
	v_mov_b32_e32 v108, v0
	v_mov_b32_e32 v109, v0
	v_mov_b32_e32 v110, v0
	v_mov_b32_e32 v111, v0
	v_mov_b32_e32 v112, v0
	v_mov_b32_e32 v113, v0
	v_mov_b32_e32 v114, v0
	v_mov_b32_e32 v115, v0
	v_mov_b32_e32 v116, v0
	v_mov_b32_e32 v117, v0
	v_mov_b32_e32 v118, v0
	v_mov_b32_e32 v119, v0
	v_mov_b32_e32 v120, v0
	v_mov_b32_e32 v121, v0
	v_mov_b32_e32 v122, v0
	v_mov_b32_e32 v123, v0
	v_mov_b32_e32 v124, v0
	v_mov_b32_e32 v125, v0
	v_mov_b32_e32 v126, v0
	v_mov_b32_e32 v127, v0
	v_mov_b32_e32 v128, v0
	v_mov_b32_e32 v129, v0
	s_and_b64 s[98:99], s[56:57], s[8:9]
	s_andn2_b64 vcc, exec, s[4:5]
	s_mov_b32 s0, s29
	s_cbranch_vccz .Lhm177_x
	s_ashr_i32 s1, s0, 31
	s_lshr_b32 s1, s1, 26
	s_add_i32 s1, s0, s1
	s_and_b32 s2, s1, 0xffffc0
	s_sub_i32 s2, s0, s2
	s_lshl_b32 s10, s2, 8
	v_readlane_b32 s2, v244, 20
	s_add_i32 s29, s0, s2
	s_cmpk_lt_i32 s29, 0xd00
	s_cselect_b64 s[8:9], -1, 0
	s_cmpk_gt_i32 s29, 0xcff
	s_cselect_b64 s[4:5], -1, 0
	s_ashr_i32 s2, s29, 31
	s_lshr_b32 s2, s2, 26
	s_add_i32 s2, s29, s2
	s_ashr_i32 s2, s2, 6
	s_and_b64 vcc, exec, s[4:5]
	s_mov_b32 s11, s10
	v_readlane_b32 s3, v244, 21
	s_cbranch_vccnz .Lhm177_0
	s_lshl_b32 s3, s2, 6
	s_sub_i32 s3, s29, s3
	s_lshl_b32 s11, s3, 8
.Lhm177_0:
	s_ashr_i32 s3, s1, 6
	s_cmpk_gt_i32 s0, 0x3bf
	s_cselect_b64 s[0:1], -1, 0
	s_cmp_lg_u64 s[0:1], 0
	s_addc_u32 s30, s3, 0
	s_lshl_b32 s0, s30, 8
	s_cmpk_gt_i32 s29, 0x3bf
	s_cselect_b64 s[6:7], -1, 0
	s_cmp_lg_u64 s[6:7], 0
	s_addc_u32 s1, s2, 0
	s_lshl_b32 s1, s1, 8
	s_and_b64 s[2:3], s[8:9], exec
	s_cselect_b32 s31, s1, s0
	s_ashr_i32 s1, s0, 31
	s_lshl_b64 s[2:3], s[0:1], 12
	s_mov_b32 s38, 0
	s_or_b32 s34, s0, 0x80
	s_or_b32 s35, s11, 0x80
	s_or_b32 s36, s10, 0x80
	s_or_b32 s37, s31, 0x80
	v_lshl_add_u64 v[134:135], v[132:133], 0, s[2:3]
	s_waitcnt vmcnt(0)
	s_andn2_b64 vcc, exec, s[98:99]
	s_cbranch_vccnz .Lhm177_k
	s_barrier
	s_branch .Lhm177_k
.Lhm177_x:
	s_waitcnt vmcnt(0)
	s_andn2_b64 vcc, exec, s[98:99]
	s_cbranch_vccnz .LBB0_270
	s_barrier
	s_branch .LBB0_270

; #define STAGE(P_, BASE, br, kt) do { const u16* _gb = (BASE) + (long)(br) * K + (long)(kt) * BK; \
;     _Pragma("unroll") for (int _i = 0; _i < 2; ++_i) { \
;       __builtin_amdgcn_global_load_lds((const unsigned*)(_gb + (long)_i * 64 * K + lane_off), \
;         (unsigned*)((char*)(P_) + lds_wbase + _i * 8192), 16, 0, 0); } } while (0)
; #define LDA(dst, b, h) _Pragma("unroll") for (int m = 0; m < 4; ++m) _Pragma("unroll") for (int k = 0; k < 2; ++k) \
;     dst[m][k] = *reinterpret_cast<const bf16x8*>((char*)SA(b, h) + lds_byte(wr * 64 + m * 16 + fr, k * 32 + fq * 8))
; #define LDB(dst, b, h) _Pragma("unroll") for (int n = 0; n < 2; ++n) _Pragma("unroll") for (int k = 0; k < 2; ++k) \
;     dst[n][k] = *reinterpret_cast<const bf16x8*>((char*)SB(b, h) + lds_byte(wc * 32 + n * 16 + fr, k * 32 + fq * 8))
; #define MMA(ai, bj, At_, Bt_) do { __builtin_amdgcn_s_setprio(1); \
;     _Pragma("unroll") for (int m = 0; m < 4; ++m) _Pragma("unroll") for (int n = 0; n < 2; ++n) _Pragma("unroll") for (int k = 0; k < 2; ++k) \
;       acc[ai][bj][m][n] = __builtin_amdgcn_mfma_f32_16x16x32_bf16(At_[m][k], Bt_[n][k], acc[ai][bj][m][n], 0, 0, 0); \
;     __builtin_amdgcn_s_setprio(0); } while (0)
; #define WAIT_V(n) asm volatile("s_waitcnt vmcnt(" #n ")" ::: "memory")
; #define BAR __builtin_amdgcn_s_barrier()
; template <int PRE> ...
;     ...
;   for (int t = 0; t < nt; t += 2) {
;     LDB(B0, 0, 0); SCHED; LDA(At, 0, 0); STAGE(SA(1, 1), A, brow + HALF, t + 1);
;     WAIT_L(8); BAR; WAIT_L(0); MMA(0, 0, At, B0); BAR; SCHED;
;     LDB(B1, 0, 1); STAGEW(SB(0, 0), Bt, bcol, bcol_n, t + 2);
;     BAR; WAIT_L(0); MMA(0, 1, At, B1); BAR;
;     LDA(At, 0, 1); STAGEW(SA(0, 0), A, brow, brow_n, t + 2);
;     BAR; WAIT_L(0); MMA(1, 0, At, B0); BAR; SCHED;
;     STAGEW(SB(0, 1), Bt, bcol + HALF, bcol_n + HALF, t + 2);
;     WAIT_V(6); BAR; MMA(1, 1, At, B1); BAR;
;     LDB(B0, 1, 0); SCHED; LDA(At, 1, 0); STAGEW(SA(0, 1), A, brow + HALF, brow_n + HALF, t + 2);
;     WAIT_L(8); BAR; WAIT_L(0); MMA(0, 0, At, B0); BAR; SCHED;
;     LDB(B1, 1, 1); STAGEW(SB(1, 0), Bt, bcol, bcol_n, t + 3);
;     BAR; WAIT_L(0); MMA(0, 1, At, B1); BAR;
;     LDA(At, 1, 1); STAGEW(SA(1, 0), A, brow, brow_n, t + 3);
;     BAR; WAIT_L(0); MMA(1, 0, At, B0); BAR; SCHED;
;     STAGEW(SB(1, 1), Bt, bcol + HALF, bcol_n + HALF, t + 3);
;     WAIT_V(6); BAR; MMA(1, 1, At, B1); BAR;
;   }
.Lhm1009_k:
.LBB0_1015:
	v_add_u32_e32 v144, s81, v135
	ds_read_b128 v[140:143], v144
	ds_read_b128 v[146:149], v144 offset:1024
	ds_read_b128 v[150:153], v144 offset:2048
	ds_read_b128 v[154:157], v144 offset:3072
	s_add_i32 m0, s10, 0xc000
	ds_read_b128 v[158:161], v136
	ds_read_b128 v[168:171], v136 offset:1024
	ds_read_b128 v[172:175], v137
	ds_read_b128 v[176:179], v137 offset:1024
	ds_read_b128 v[180:183], v138
	ds_read_b128 v[184:187], v138 offset:1024
	ds_read_b128 v[188:191], v139
	ds_read_b128 v[192:195], v139 offset:1024
	global_load_lds_dwordx4 v[132:133], off
	v_lshl_add_u64 v[162:163], v[132:133], 0, s[86:87]
	s_add_i32 m0, s10, 0xe000
	s_nop 0
	global_load_lds_dwordx4 v[162:163], off
	s_waitcnt lgkmcnt(8)
	s_barrier
	s_waitcnt lgkmcnt(0)
	v_mfma_f32_16x16x32_bf16 v[124:127], v[158:161], v[140:143], v[124:127]
	v_mfma_f32_16x16x32_bf16 v[116:119], v[158:161], v[150:153], v[116:119]
	v_mfma_f32_16x16x32_bf16 v[108:111], v[172:175], v[140:143], v[108:111]
	v_mfma_f32_16x16x32_bf16 v[100:103], v[172:175], v[150:153], v[100:103]
	v_mfma_f32_16x16x32_bf16 v[92:95], v[180:183], v[140:143], v[92:95]
	v_mfma_f32_16x16x32_bf16 v[84:87], v[180:183], v[150:153], v[84:87]
	v_mfma_f32_16x16x32_bf16 v[76:79], v[188:191], v[140:143], v[76:79]
	v_mfma_f32_16x16x32_bf16 v[68:71], v[188:191], v[150:153], v[68:71]
	v_mfma_f32_16x16x32_bf16 v[124:127], v[168:171], v[146:149], v[124:127]
	v_mfma_f32_16x16x32_bf16 v[116:119], v[168:171], v[154:157], v[116:119]
	v_mfma_f32_16x16x32_bf16 v[108:111], v[176:179], v[146:149], v[108:111]
	v_mfma_f32_16x16x32_bf16 v[100:103], v[176:179], v[154:157], v[100:103]
	v_mfma_f32_16x16x32_bf16 v[92:95], v[184:187], v[146:149], v[92:95]
	v_mfma_f32_16x16x32_bf16 v[84:87], v[184:187], v[154:157], v[84:87]
	v_mfma_f32_16x16x32_bf16 v[76:79], v[192:195], v[146:149], v[76:79]
	v_mfma_f32_16x16x32_bf16 v[68:71], v[192:195], v[154:157], v[68:71]
	s_barrier
	s_add_i32 s37, s1, 2
	s_cmp_lt_u32 s1, 30
	s_cselect_b64 s[2:3], -1, 0
	s_and_b64 vcc, s[2:3], exec
	s_cselect_b32 s4, s27, s30
	s_cselect_b32 s3, 0, 0xffffffe0
	s_cselect_b32 s38, s0, s29
	s_cselect_b32 s40, s35, s34
	s_cselect_b32 s2, s31, s36
	s_ashr_i32 s5, s4, 31
	s_lshl_b64 s[4:5], s[4:5], 12
	s_add_u32 s39, s76, s4
	s_addc_u32 s41, s77, s5
	s_add_i32 s18, s37, s3
	s_lshl_b64 s[4:5], s[18:19], 7
	s_add_u32 s42, s39, s4
	s_addc_u32 s43, s41, s5
	s_mov_b32 m0, s11
	v_add_u32_e32 v144, s82, v135
	v_lshl_add_u64 v[162:163], s[42:43], 0, v[128:129]
	ds_read_b128 v[210:213], v144
	ds_read_b128 v[214:217], v144 offset:1024
	ds_read_b128 v[218:221], v144 offset:2048
	ds_read_b128 v[222:225], v144 offset:3072
	global_load_lds_dwordx4 v[162:163], off
	v_lshl_add_u64 v[162:163], v[162:163], 0, s[86:87]
	s_mov_b32 m0, s12
	s_nop 0
	global_load_lds_dwordx4 v[162:163], off
	s_barrier
	s_waitcnt lgkmcnt(0)
	v_mfma_f32_16x16x32_bf16 v[60:63], v[158:161], v[210:213], v[60:63]
	v_mfma_f32_16x16x32_bf16 v[52:55], v[158:161], v[218:221], v[52:55]
	v_mfma_f32_16x16x32_bf16 v[44:47], v[172:175], v[210:213], v[44:47]
	v_mfma_f32_16x16x32_bf16 v[36:39], v[172:175], v[218:221], v[36:39]
	v_mfma_f32_16x16x32_bf16 v[28:31], v[180:183], v[210:213], v[28:31]
	v_mfma_f32_16x16x32_bf16 v[20:23], v[180:183], v[218:221], v[20:23]
	v_mfma_f32_16x16x32_bf16 v[12:15], v[188:191], v[210:213], v[12:15]
	v_mfma_f32_16x16x32_bf16 v[4:7], v[188:191], v[218:221], v[4:7]
	v_mfma_f32_16x16x32_bf16 v[60:63], v[168:171], v[214:217], v[60:63]
	v_mfma_f32_16x16x32_bf16 v[52:55], v[168:171], v[222:225], v[52:55]
	v_mfma_f32_16x16x32_bf16 v[44:47], v[176:179], v[214:217], v[44:47]
	v_mfma_f32_16x16x32_bf16 v[36:39], v[176:179], v[222:225], v[36:39]
	v_mfma_f32_16x16x32_bf16 v[28:31], v[184:187], v[214:217], v[28:31]
	v_mfma_f32_16x16x32_bf16 v[20:23], v[184:187], v[222:225], v[20:23]
	v_mfma_f32_16x16x32_bf16 v[12:15], v[192:195], v[214:217], v[12:15]
	v_mfma_f32_16x16x32_bf16 v[4:7], v[192:195], v[222:225], v[4:7]
	s_ashr_i32 s39, s38, 31
	s_lshl_b64 s[38:39], s[38:39], 12
	s_add_u32 s3, s75, s38
	s_addc_u32 s18, s78, s39
	s_add_u32 s38, s3, s4
	s_addc_u32 s39, s18, s5
	s_mov_b32 m0, s10
	v_lshl_add_u64 v[162:163], s[38:39], 0, v[128:129]
	s_barrier
	ds_read_b128 v[158:161], v136 offset:16384
	ds_read_b128 v[168:171], v136 offset:17408
	ds_read_b128 v[172:175], v137 offset:16384
	ds_read_b128 v[176:179], v137 offset:17408
	ds_read_b128 v[180:183], v138 offset:16384
	ds_read_b128 v[184:187], v138 offset:17408
	ds_read_b128 v[188:191], v139 offset:16384
	ds_read_b128 v[192:195], v139 offset:17408
	global_load_lds_dwordx4 v[162:163], off
	v_lshl_add_u64 v[162:163], v[162:163], 0, s[86:87]
	s_mov_b32 m0, s13
	s_nop 0
	global_load_lds_dwordx4 v[162:163], off
	s_barrier
	s_waitcnt lgkmcnt(0)
	v_mfma_f32_16x16x32_bf16 v[120:123], v[158:161], v[140:143], v[120:123]
	v_mfma_f32_16x16x32_bf16 v[112:115], v[158:161], v[150:153], v[112:115]
	v_mfma_f32_16x16x32_bf16 v[104:107], v[172:175], v[140:143], v[104:107]
	v_mfma_f32_16x16x32_bf16 v[96:99], v[172:175], v[150:153], v[96:99]
	v_mfma_f32_16x16x32_bf16 v[88:91], v[180:183], v[140:143], v[88:91]
	v_mfma_f32_16x16x32_bf16 v[80:83], v[180:183], v[150:153], v[80:83]
	v_mfma_f32_16x16x32_bf16 v[72:75], v[188:191], v[140:143], v[72:75]
	v_mfma_f32_16x16x32_bf16 v[64:67], v[188:191], v[150:153], v[64:67]
	v_mfma_f32_16x16x32_bf16 v[120:123], v[168:171], v[146:149], v[120:123]
	v_mfma_f32_16x16x32_bf16 v[112:115], v[168:171], v[154:157], v[112:115]
	v_mfma_f32_16x16x32_bf16 v[104:107], v[176:179], v[146:149], v[104:107]
	v_mfma_f32_16x16x32_bf16 v[96:99], v[176:179], v[154:157], v[96:99]
	v_mfma_f32_16x16x32_bf16 v[88:91], v[184:187], v[146:149], v[88:91]
	v_mfma_f32_16x16x32_bf16 v[80:83], v[184:187], v[154:157], v[80:83]
	v_mfma_f32_16x16x32_bf16 v[72:75], v[192:195], v[146:149], v[72:75]
	v_mfma_f32_16x16x32_bf16 v[64:67], v[192:195], v[154:157], v[64:67]
	s_barrier
; #define STAGE(P_, BASE, br, kt) do { const u16* _gb = (BASE) + (long)(br) * K + (long)(kt) * BK; \
;     _Pragma("unroll") for (int _i = 0; _i < 2; ++_i) { \
;       __builtin_amdgcn_global_load_lds((const unsigned*)(_gb + (long)_i * 64 * K + lane_off), \
;         (unsigned*)((char*)(P_) + lds_wbase + _i * 8192), 16, 0, 0); } } while (0)
; #define LDA(dst, b, h) _Pragma("unroll") for (int m = 0; m < 4; ++m) _Pragma("unroll") for (int k = 0; k < 2; ++k) \
;     dst[m][k] = *reinterpret_cast<const bf16x8*>((char*)SA(b, h) + lds_byte(wr * 64 + m * 16 + fr, k * 32 + fq * 8))
; #define LDB(dst, b, h) _Pragma("unroll") for (int n = 0; n < 2; ++n) _Pragma("unroll") for (int k = 0; k < 2; ++k) \
;     dst[n][k] = *reinterpret_cast<const bf16x8*>((char*)SB(b, h) + lds_byte(wc * 32 + n * 16 + fr, k * 32 + fq * 8))
; #define MMA(ai, bj, At_, Bt_) do { __builtin_amdgcn_s_setprio(1); \
;     _Pragma("unroll") for (int m = 0; m < 4; ++m) _Pragma("unroll") for (int n = 0; n < 2; ++n) _Pragma("unroll") for (int k = 0; k < 2; ++k) \
;       acc[ai][bj][m][n] = __builtin_amdgcn_mfma_f32_16x16x32_bf16(At_[m][k], Bt_[n][k], acc[ai][bj][m][n], 0, 0, 0); \
;     __builtin_amdgcn_s_setprio(0); } while (0)
; #define WAIT_V(n) asm volatile("s_waitcnt vmcnt(" #n ")" ::: "memory")
; #define BAR __builtin_amdgcn_s_barrier()
; template <int PRE> ...
;     ...
;   for (int t = 0; t < nt; t += 2) {
;     LDB(B0, 0, 0); SCHED; LDA(At, 0, 0); STAGE(SA(1, 1), A, brow + HALF, t + 1);
;     WAIT_L(8); BAR; WAIT_L(0); MMA(0, 0, At, B0); BAR; SCHED;
;     LDB(B1, 0, 1); STAGEW(SB(0, 0), Bt, bcol, bcol_n, t + 2);
;     BAR; WAIT_L(0); MMA(0, 1, At, B1); BAR;
;     LDA(At, 0, 1); STAGEW(SA(0, 0), A, brow, brow_n, t + 2);
;     BAR; WAIT_L(0); MMA(1, 0, At, B0); BAR; SCHED;
;     STAGEW(SB(0, 1), Bt, bcol + HALF, bcol_n + HALF, t + 2);
;     WAIT_V(6); BAR; MMA(1, 1, At, B1); BAR;
;     LDB(B0, 1, 0); SCHED; LDA(At, 1, 0); STAGEW(SA(0, 1), A, brow + HALF, brow_n + HALF, t + 2);
;     WAIT_L(8); BAR; WAIT_L(0); MMA(0, 0, At, B0); BAR; SCHED;
;     LDB(B1, 1, 1); STAGEW(SB(1, 0), Bt, bcol, bcol_n, t + 3);
;     BAR; WAIT_L(0); MMA(0, 1, At, B1); BAR;
;     LDA(At, 1, 1); STAGEW(SA(1, 0), A, brow, brow_n, t + 3);
;     BAR; WAIT_L(0); MMA(1, 0, At, B0); BAR; SCHED;
;     STAGEW(SB(1, 1), Bt, bcol + HALF, bcol_n + HALF, t + 3);
;     WAIT_V(6); BAR; MMA(1, 1, At, B1); BAR;
;   }
	s_ashr_i32 s41, s40, 31
	s_lshl_b64 s[38:39], s[40:41], 12
	s_add_u32 s3, s76, s38
	s_addc_u32 s18, s77, s39
	s_add_u32 s38, s3, s4
	s_addc_u32 s39, s18, s5
	s_mov_b32 m0, s14
	v_lshl_add_u64 v[140:141], s[38:39], 0, v[128:129]
	global_load_lds_dwordx4 v[140:141], off
	v_lshl_add_u64 v[140:141], v[140:141], 0, s[86:87]
	s_mov_b32 m0, s15
	s_nop 0
	global_load_lds_dwordx4 v[140:141], off
	s_waitcnt vmcnt(6)
	s_barrier
	v_mfma_f32_16x16x32_bf16 v[56:59], v[158:161], v[210:213], v[56:59]
	v_mfma_f32_16x16x32_bf16 v[48:51], v[158:161], v[218:221], v[48:51]
	v_mfma_f32_16x16x32_bf16 v[40:43], v[172:175], v[210:213], v[40:43]
	v_mfma_f32_16x16x32_bf16 v[32:35], v[172:175], v[218:221], v[32:35]
	v_mfma_f32_16x16x32_bf16 v[24:27], v[180:183], v[210:213], v[24:27]
	v_mfma_f32_16x16x32_bf16 v[16:19], v[180:183], v[218:221], v[16:19]
	v_mfma_f32_16x16x32_bf16 v[8:11], v[188:191], v[210:213], v[8:11]
	v_mfma_f32_16x16x32_bf16 v[0:3], v[188:191], v[218:221], v[0:3]
	v_mfma_f32_16x16x32_bf16 v[56:59], v[168:171], v[214:217], v[56:59]
	v_mfma_f32_16x16x32_bf16 v[48:51], v[168:171], v[222:225], v[48:51]
	v_mfma_f32_16x16x32_bf16 v[40:43], v[176:179], v[214:217], v[40:43]
	v_mfma_f32_16x16x32_bf16 v[32:35], v[176:179], v[222:225], v[32:35]
	v_mfma_f32_16x16x32_bf16 v[24:27], v[184:187], v[214:217], v[24:27]
	v_mfma_f32_16x16x32_bf16 v[16:19], v[184:187], v[222:225], v[16:19]
	v_mfma_f32_16x16x32_bf16 v[8:11], v[192:195], v[214:217], v[8:11]
	v_mfma_f32_16x16x32_bf16 v[0:3], v[192:195], v[222:225], v[0:3]
	v_add_u32_e32 v144, s83, v135
	s_barrier
	ds_read_b128 v[140:143], v144
	ds_read_b128 v[146:149], v144 offset:1024
	ds_read_b128 v[150:153], v144 offset:2048
	ds_read_b128 v[154:157], v144 offset:3072
	s_ashr_i32 s3, s2, 31
	s_lshl_b64 s[2:3], s[2:3], 12
	s_add_u32 s2, s75, s2
	s_addc_u32 s3, s78, s3
	s_add_u32 s2, s2, s4
	s_addc_u32 s3, s3, s5
	s_mov_b32 m0, s16
	v_lshl_add_u64 v[162:163], s[2:3], 0, v[128:129]
	ds_read_b128 v[158:161], v136 offset:32768
	ds_read_b128 v[168:171], v136 offset:33792
	ds_read_b128 v[172:175], v137 offset:32768
	ds_read_b128 v[176:179], v137 offset:33792
	ds_read_b128 v[180:183], v138 offset:32768
	ds_read_b128 v[184:187], v138 offset:33792
	ds_read_b128 v[188:191], v139 offset:32768
	ds_read_b128 v[192:195], v139 offset:33792
	global_load_lds_dwordx4 v[162:163], off
	v_lshl_add_u64 v[162:163], v[162:163], 0, s[86:87]
	s_mov_b32 m0, s17
	s_nop 0
	global_load_lds_dwordx4 v[162:163], off
	s_waitcnt lgkmcnt(8)
	s_barrier
	s_waitcnt lgkmcnt(0)
	v_mfma_f32_16x16x32_bf16 v[124:127], v[158:161], v[140:143], v[124:127]
	v_mfma_f32_16x16x32_bf16 v[116:119], v[158:161], v[150:153], v[116:119]
	v_mfma_f32_16x16x32_bf16 v[108:111], v[172:175], v[140:143], v[108:111]
	v_mfma_f32_16x16x32_bf16 v[100:103], v[172:175], v[150:153], v[100:103]
	v_mfma_f32_16x16x32_bf16 v[92:95], v[180:183], v[140:143], v[92:95]
	v_mfma_f32_16x16x32_bf16 v[84:87], v[180:183], v[150:153], v[84:87]
	v_mfma_f32_16x16x32_bf16 v[76:79], v[188:191], v[140:143], v[76:79]
	v_mfma_f32_16x16x32_bf16 v[68:71], v[188:191], v[150:153], v[68:71]
	v_mfma_f32_16x16x32_bf16 v[124:127], v[168:171], v[146:149], v[124:127]
	v_mfma_f32_16x16x32_bf16 v[116:119], v[168:171], v[154:157], v[116:119]
	v_mfma_f32_16x16x32_bf16 v[108:111], v[176:179], v[146:149], v[108:111]
	v_mfma_f32_16x16x32_bf16 v[100:103], v[176:179], v[154:157], v[100:103]
	v_mfma_f32_16x16x32_bf16 v[92:95], v[184:187], v[146:149], v[92:95]
	v_mfma_f32_16x16x32_bf16 v[84:87], v[184:187], v[154:157], v[84:87]
	v_mfma_f32_16x16x32_bf16 v[76:79], v[192:195], v[146:149], v[76:79]
	v_mfma_f32_16x16x32_bf16 v[68:71], v[192:195], v[154:157], v[68:71]
	s_barrier
	s_cmp_lt_u32 s1, 29
	s_cselect_b32 s2, s27, s30
	s_cselect_b32 s5, 0, 0xffffffe0
	s_cselect_b32 s4, s0, s29
	s_cselect_b32 s38, s35, s34
	s_ashr_i32 s3, s2, 31
	s_lshl_b64 s[2:3], s[2:3], 12
	s_add_u32 s39, s76, s2
	s_addc_u32 s41, s77, s3
	s_add_i32 s1, s5, s1
	s_add_i32 s18, s1, 3
	s_lshl_b64 s[2:3], s[18:19], 7
	s_add_u32 s40, s39, s2
	s_addc_u32 s41, s41, s3
	s_mov_b32 m0, s20
	v_add_u32_e32 v144, s84, v135
	v_lshl_add_u64 v[162:163], s[40:41], 0, v[128:129]
	ds_read_b128 v[210:213], v144
	ds_read_b128 v[214:217], v144 offset:1024
	ds_read_b128 v[218:221], v144 offset:2048
	ds_read_b128 v[222:225], v144 offset:3072
	global_load_lds_dwordx4 v[162:163], off
	v_lshl_add_u64 v[162:163], v[162:163], 0, s[86:87]
	s_mov_b32 m0, s21
	s_nop 0
	global_load_lds_dwordx4 v[162:163], off
	s_barrier
	s_waitcnt lgkmcnt(0)
	v_mfma_f32_16x16x32_bf16 v[60:63], v[158:161], v[210:213], v[60:63]
	v_mfma_f32_16x16x32_bf16 v[52:55], v[158:161], v[218:221], v[52:55]
	v_mfma_f32_16x16x32_bf16 v[44:47], v[172:175], v[210:213], v[44:47]
	v_mfma_f32_16x16x32_bf16 v[36:39], v[172:175], v[218:221], v[36:39]
	v_mfma_f32_16x16x32_bf16 v[28:31], v[180:183], v[210:213], v[28:31]
	v_mfma_f32_16x16x32_bf16 v[20:23], v[180:183], v[218:221], v[20:23]
	v_mfma_f32_16x16x32_bf16 v[12:15], v[188:191], v[210:213], v[12:15]
	v_mfma_f32_16x16x32_bf16 v[4:7], v[188:191], v[218:221], v[4:7]
	v_mfma_f32_16x16x32_bf16 v[60:63], v[168:171], v[214:217], v[60:63]
	v_mfma_f32_16x16x32_bf16 v[52:55], v[168:171], v[222:225], v[52:55]
	v_mfma_f32_16x16x32_bf16 v[44:47], v[176:179], v[214:217], v[44:47]
	v_mfma_f32_16x16x32_bf16 v[36:39], v[176:179], v[222:225], v[36:39]
	v_mfma_f32_16x16x32_bf16 v[28:31], v[184:187], v[214:217], v[28:31]
	v_mfma_f32_16x16x32_bf16 v[20:23], v[184:187], v[222:225], v[20:23]
	v_mfma_f32_16x16x32_bf16 v[12:15], v[192:195], v[214:217], v[12:15]
	v_mfma_f32_16x16x32_bf16 v[4:7], v[192:195], v[222:225], v[4:7]
	s_ashr_i32 s5, s4, 31
	s_lshl_b64 s[4:5], s[4:5], 12
	s_add_u32 s1, s75, s4
	s_addc_u32 s5, s78, s5
	s_add_u32 s4, s1, s2
	s_addc_u32 s5, s5, s3
	s_mov_b32 m0, s22
	v_lshl_add_u64 v[162:163], s[4:5], 0, v[128:129]
	s_barrier
; __device__ __forceinline__ float siluf_(float x) { return x * __builtin_amdgcn_rcpf(1.f + __expf(-x)); }
; #define MMA(ai, bj, At_, Bt_) do { __builtin_amdgcn_s_setprio(1); \
;     _Pragma("unroll") for (int m = 0; m < 4; ++m) _Pragma("unroll") for (int n = 0; n < 2; ++n) _Pragma("unroll") for (int k = 0; k < 2; ++k) \
;       acc[ai][bj][m][n] = __builtin_amdgcn_mfma_f32_16x16x32_bf16(At_[m][k], Bt_[n][k], acc[ai][bj][m][n], 0, 0, 0); \
;     __builtin_amdgcn_s_setprio(0); } while (0)
; #define WAIT_V(n) asm volatile("s_waitcnt vmcnt(" #n ")" ::: "memory")
; #define WAIT_L(n) asm volatile("s_waitcnt lgkmcnt(" #n ")" ::: "memory")
; #define BAR __builtin_amdgcn_s_barrier()
; #define SCHED __builtin_amdgcn_sched_barrier(0)
; #define STAGEW(P_, BASE, cur, nxt, kt_) do { const bool _wr = (kt_) >= nt; \
;     STAGE(P_, BASE, (_wr ? (nxt) : (cur)), (_wr ? (kt_) - nt : (kt_))); } while (0)
; template <int PRE> ...
;     ...
;     BAR; WAIT_L(0); MMA(1, 0, At, B0); BAR; SCHED;
;     STAGEW(SB(1, 1), Bt, bcol + HALF, bcol_n + HALF, t + 3);
;     WAIT_V(6); BAR; MMA(1, 1, At, B1); BAR;
;   }
;   if (wr == 0) BAR;
;     ...
;     if (MODE == 4) {
;       u16* act = (u16*)(ws + OFF_RA);
;       uint2 opend4[2];
; #pragma unroll
;       for (int bj = 0; bj < 2; ++bj)
; #pragma unroll
;         for (int m = 0; m < 4; ++m)
; #pragma unroll
;           for (int n = 0; n < 2; ++n) {
;             int lane_i = lane_e;
;             asm volatile("" : "+v"(lane_i));
;             const int fr = lane_i & 15, fq = lane_i >> 4;
;             const int nc = tn * 128 + wr * 64 + m * 16 + fq * 4;
;             const int tok = bcol + bj * 128 + wc * 32 + n * 16 + fr;
;             f32x4 g = acc[0][bj][m][n], up = acc[1][bj][m][n];
;             uint2 o;
;             o.x = pk2(siluf_(g[0]) * up[0], siluf_(g[1]) * up[1]);
;             o.y = pk2(siluf_(g[2]) * up[2], siluf_(g[3]) * up[3]);
;             if ((m & 1) == 0) opend4[n] = o;
;             else {
;               const int ncw = tn * 128 + wr * 64 + ((m & ~1) + (fq & 1)) * 16 + (fq & ~1) * 4;
;               *(uint4*)(act + (size_t)tok * DFF + ncw) = swap_pair(opend4[n], o);
;             }
	ds_read_b128 v[158:161], v136 offset:49152
	ds_read_b128 v[168:171], v136 offset:50176
	ds_read_b128 v[172:175], v137 offset:49152
	ds_read_b128 v[176:179], v137 offset:50176
	ds_read_b128 v[180:183], v138 offset:49152
	ds_read_b128 v[184:187], v138 offset:50176
	ds_read_b128 v[188:191], v139 offset:49152
	ds_read_b128 v[192:195], v139 offset:50176
	global_load_lds_dwordx4 v[162:163], off
	v_lshl_add_u64 v[162:163], v[162:163], 0, s[86:87]
	s_mov_b32 m0, s23
	s_nop 0
	global_load_lds_dwordx4 v[162:163], off
	s_barrier
	s_waitcnt lgkmcnt(0)
	v_mfma_f32_16x16x32_bf16 v[120:123], v[158:161], v[140:143], v[120:123]
	v_mfma_f32_16x16x32_bf16 v[112:115], v[158:161], v[150:153], v[112:115]
	v_mfma_f32_16x16x32_bf16 v[104:107], v[172:175], v[140:143], v[104:107]
	v_mfma_f32_16x16x32_bf16 v[96:99], v[172:175], v[150:153], v[96:99]
	v_mfma_f32_16x16x32_bf16 v[88:91], v[180:183], v[140:143], v[88:91]
	v_mfma_f32_16x16x32_bf16 v[80:83], v[180:183], v[150:153], v[80:83]
	v_mfma_f32_16x16x32_bf16 v[72:75], v[188:191], v[140:143], v[72:75]
	v_mfma_f32_16x16x32_bf16 v[64:67], v[188:191], v[150:153], v[64:67]
	v_mfma_f32_16x16x32_bf16 v[120:123], v[168:171], v[146:149], v[120:123]
	v_mfma_f32_16x16x32_bf16 v[112:115], v[168:171], v[154:157], v[112:115]
	v_mfma_f32_16x16x32_bf16 v[104:107], v[176:179], v[146:149], v[104:107]
	v_mfma_f32_16x16x32_bf16 v[96:99], v[176:179], v[154:157], v[96:99]
	v_mfma_f32_16x16x32_bf16 v[88:91], v[184:187], v[146:149], v[88:91]
	v_mfma_f32_16x16x32_bf16 v[80:83], v[184:187], v[154:157], v[80:83]
	v_mfma_f32_16x16x32_bf16 v[72:75], v[192:195], v[146:149], v[72:75]
	v_mfma_f32_16x16x32_bf16 v[64:67], v[192:195], v[154:157], v[64:67]
	s_barrier
	s_ashr_i32 s39, s38, 31
	s_lshl_b64 s[4:5], s[38:39], 12
	s_add_u32 s1, s76, s4
	s_addc_u32 s4, s77, s5
	s_add_u32 s2, s1, s2
	s_addc_u32 s3, s4, s3
	s_mov_b32 m0, s24
	v_lshl_add_u64 v[140:141], s[2:3], 0, v[128:129]
	global_load_lds_dwordx4 v[140:141], off
	v_lshl_add_u64 v[140:141], v[140:141], 0, s[86:87]
	s_mov_b32 m0, s25
	s_nop 0
	global_load_lds_dwordx4 v[140:141], off
	s_waitcnt vmcnt(6)
	s_barrier
	v_mfma_f32_16x16x32_bf16 v[56:59], v[158:161], v[210:213], v[56:59]
	v_mfma_f32_16x16x32_bf16 v[48:51], v[158:161], v[218:221], v[48:51]
	v_mfma_f32_16x16x32_bf16 v[40:43], v[172:175], v[210:213], v[40:43]
	v_mfma_f32_16x16x32_bf16 v[32:35], v[172:175], v[218:221], v[32:35]
	v_mfma_f32_16x16x32_bf16 v[24:27], v[180:183], v[210:213], v[24:27]
	v_mfma_f32_16x16x32_bf16 v[16:19], v[180:183], v[218:221], v[16:19]
	v_mfma_f32_16x16x32_bf16 v[8:11], v[188:191], v[210:213], v[8:11]
	v_mfma_f32_16x16x32_bf16 v[0:3], v[188:191], v[218:221], v[0:3]
	v_mfma_f32_16x16x32_bf16 v[56:59], v[168:171], v[214:217], v[56:59]
	v_mfma_f32_16x16x32_bf16 v[48:51], v[168:171], v[222:225], v[48:51]
	v_mfma_f32_16x16x32_bf16 v[40:43], v[176:179], v[214:217], v[40:43]
	v_mfma_f32_16x16x32_bf16 v[32:35], v[176:179], v[222:225], v[32:35]
	v_mfma_f32_16x16x32_bf16 v[24:27], v[184:187], v[214:217], v[24:27]
	v_mfma_f32_16x16x32_bf16 v[16:19], v[184:187], v[222:225], v[16:19]
	v_mfma_f32_16x16x32_bf16 v[8:11], v[192:195], v[214:217], v[8:11]
	v_mfma_f32_16x16x32_bf16 v[0:3], v[192:195], v[222:225], v[0:3]
	v_lshl_add_u64 v[132:133], v[132:133], 0, s[46:47]
	s_mov_b32 s1, s37
	s_barrier
	s_cbranch_vccnz .LBB0_1015
	v_readlane_b32 s34, v243, 2
	s_andn2_b64 vcc, exec, s[58:59]
	v_readlane_b32 s31, v244, 61
	v_readlane_b32 s35, v243, 3
	s_cbranch_vccnz .LBB0_1018
	s_barrier
.LBB0_1018:
	v_mov_b32_e32 v250, 0xbfb8aa3b
	v_mov_b32_e32 v252, 1.0
	s_or_b32 s0, s27, s54
	s_lshl_b32 s1, s28, 7
	s_add_i32 s1, s1, s49
	s_movk_i32 s3, 0x2c00
	v_and_or_b32 v132, v134, 15, s0
	v_and_or_b32 v133, v134, 16, s1
	v_ashrrev_i32_e32 v140, 2, v134
	v_and_b32_e32 v140, -8, v140
	v_add_u32_e32 v133, v133, v140
	v_lshlrev_b32_e32 v133, 1, v133
	v_mad_u32_u24 v247, v132, s3, v133
	v_add_u32_e32 v248, 0x2c000, v247
	v_add_u32_e32 v249, 0x160000, v247
	v_add_u32_e32 v254, 0x18c000, v247
	v_pk_mul_f32 v[132:133], v[124:125], v[250:251] op_sel_hi:[1,0]
	v_pk_mul_f32 v[140:141], v[126:127], v[250:251] op_sel_hi:[1,0]
	v_exp_f32_e32 v132, v132
	v_exp_f32_e32 v133, v133
	v_exp_f32_e32 v140, v140
	v_exp_f32_e32 v141, v141
	v_pk_add_f32 v[132:133], v[132:133], v[252:253] op_sel_hi:[1,0]
	v_pk_add_f32 v[140:141], v[140:141], v[252:253] op_sel_hi:[1,0]
	v_rcp_f32_e32 v132, v132
	v_rcp_f32_e32 v133, v133
	v_rcp_f32_e32 v140, v140
	v_rcp_f32_e32 v141, v141
	v_pk_mul_f32 v[124:125], v[124:125], v[132:133]
	v_pk_mul_f32 v[126:127], v[126:127], v[140:141]
	v_pk_mul_f32 v[124:125], v[124:125], v[120:121]
	v_pk_mul_f32 v[126:127], v[126:127], v[122:123]
	v_cvt_pk_bf16_f32 v124, v124, v125
	v_cvt_pk_bf16_f32 v125, v126, v127
	v_pk_mul_f32 v[132:133], v[108:109], v[250:251] op_sel_hi:[1,0]
	v_pk_mul_f32 v[140:141], v[110:111], v[250:251] op_sel_hi:[1,0]
	v_exp_f32_e32 v132, v132
	v_exp_f32_e32 v133, v133
	v_exp_f32_e32 v140, v140
	v_exp_f32_e32 v141, v141
	v_pk_add_f32 v[132:133], v[132:133], v[252:253] op_sel_hi:[1,0]
	v_pk_add_f32 v[140:141], v[140:141], v[252:253] op_sel_hi:[1,0]
	v_rcp_f32_e32 v132, v132
	v_rcp_f32_e32 v133, v133
	v_rcp_f32_e32 v140, v140
	v_rcp_f32_e32 v141, v141
	v_pk_mul_f32 v[108:109], v[108:109], v[132:133]
	v_pk_mul_f32 v[110:111], v[110:111], v[140:141]
	v_pk_mul_f32 v[108:109], v[108:109], v[104:105]
	v_pk_mul_f32 v[110:111], v[110:111], v[106:107]
	v_cvt_pk_bf16_f32 v126, v108, v109
	v_cvt_pk_bf16_f32 v127, v110, v111
	s_nop 1
	v_permlane16_swap_b32_e32 v125, v127
	v_permlane16_swap_b32_e32 v124, v126
	global_store_dwordx4 v247, v[124:127], s[66:67]
	v_pk_mul_f32 v[132:133], v[116:117], v[250:251] op_sel_hi:[1,0]
; __device__ __forceinline__ float siluf_(float x) { return x * __builtin_amdgcn_rcpf(1.f + __expf(-x)); }
;     ...
;     if (MODE == 4) {
;       u16* act = (u16*)(ws + OFF_RA);
;       uint2 opend4[2];
; #pragma unroll
;       for (int bj = 0; bj < 2; ++bj)
; #pragma unroll
;         for (int m = 0; m < 4; ++m)
; #pragma unroll
;           for (int n = 0; n < 2; ++n) {
;             int lane_i = lane_e;
;             asm volatile("" : "+v"(lane_i));
;             const int fr = lane_i & 15, fq = lane_i >> 4;
;             const int nc = tn * 128 + wr * 64 + m * 16 + fq * 4;
;             const int tok = bcol + bj * 128 + wc * 32 + n * 16 + fr;
;             f32x4 g = acc[0][bj][m][n], up = acc[1][bj][m][n];
;             uint2 o;
;             o.x = pk2(siluf_(g[0]) * up[0], siluf_(g[1]) * up[1]);
;             o.y = pk2(siluf_(g[2]) * up[2], siluf_(g[3]) * up[3]);
;             if ((m & 1) == 0) opend4[n] = o;
;             else {
;               const int ncw = tn * 128 + wr * 64 + ((m & ~1) + (fq & 1)) * 16 + (fq & ~1) * 4;
;               *(uint4*)(act + (size_t)tok * DFF + ncw) = swap_pair(opend4[n], o);
;             }
	v_pk_mul_f32 v[140:141], v[118:119], v[250:251] op_sel_hi:[1,0]
	v_exp_f32_e32 v132, v132
	v_exp_f32_e32 v133, v133
	v_exp_f32_e32 v140, v140
	v_exp_f32_e32 v141, v141
	v_pk_add_f32 v[132:133], v[132:133], v[252:253] op_sel_hi:[1,0]
	v_pk_add_f32 v[140:141], v[140:141], v[252:253] op_sel_hi:[1,0]
	v_rcp_f32_e32 v132, v132
	v_rcp_f32_e32 v133, v133
	v_rcp_f32_e32 v140, v140
	v_rcp_f32_e32 v141, v141
	v_pk_mul_f32 v[116:117], v[116:117], v[132:133]
	v_pk_mul_f32 v[118:119], v[118:119], v[140:141]
	v_pk_mul_f32 v[116:117], v[116:117], v[112:113]
	v_pk_mul_f32 v[118:119], v[118:119], v[114:115]
	v_cvt_pk_bf16_f32 v116, v116, v117
	v_cvt_pk_bf16_f32 v117, v118, v119
	v_pk_mul_f32 v[132:133], v[100:101], v[250:251] op_sel_hi:[1,0]
	v_pk_mul_f32 v[140:141], v[102:103], v[250:251] op_sel_hi:[1,0]
	v_exp_f32_e32 v132, v132
	v_exp_f32_e32 v133, v133
	v_exp_f32_e32 v140, v140
	v_exp_f32_e32 v141, v141
	v_pk_add_f32 v[132:133], v[132:133], v[252:253] op_sel_hi:[1,0]
	v_pk_add_f32 v[140:141], v[140:141], v[252:253] op_sel_hi:[1,0]
	v_rcp_f32_e32 v132, v132
	v_rcp_f32_e32 v133, v133
	v_rcp_f32_e32 v140, v140
	v_rcp_f32_e32 v141, v141
	v_pk_mul_f32 v[100:101], v[100:101], v[132:133]
	v_pk_mul_f32 v[102:103], v[102:103], v[140:141]
	v_pk_mul_f32 v[100:101], v[100:101], v[96:97]
	v_pk_mul_f32 v[102:103], v[102:103], v[98:99]
	v_cvt_pk_bf16_f32 v118, v100, v101
	v_cvt_pk_bf16_f32 v119, v102, v103
	s_nop 1
	v_permlane16_swap_b32_e32 v117, v119
	v_permlane16_swap_b32_e32 v116, v118
	global_store_dwordx4 v248, v[116:119], s[66:67]
	v_pk_mul_f32 v[132:133], v[92:93], v[250:251] op_sel_hi:[1,0]
	v_pk_mul_f32 v[140:141], v[94:95], v[250:251] op_sel_hi:[1,0]
	v_exp_f32_e32 v132, v132
	v_exp_f32_e32 v133, v133
	v_exp_f32_e32 v140, v140
	v_exp_f32_e32 v141, v141
	v_pk_add_f32 v[132:133], v[132:133], v[252:253] op_sel_hi:[1,0]
	v_pk_add_f32 v[140:141], v[140:141], v[252:253] op_sel_hi:[1,0]
	v_rcp_f32_e32 v132, v132
	v_rcp_f32_e32 v133, v133
	v_rcp_f32_e32 v140, v140
	v_rcp_f32_e32 v141, v141
	v_pk_mul_f32 v[92:93], v[92:93], v[132:133]
	v_pk_mul_f32 v[94:95], v[94:95], v[140:141]
	v_pk_mul_f32 v[92:93], v[92:93], v[88:89]
	v_pk_mul_f32 v[94:95], v[94:95], v[90:91]
	v_cvt_pk_bf16_f32 v92, v92, v93
	v_cvt_pk_bf16_f32 v93, v94, v95
	v_pk_mul_f32 v[132:133], v[76:77], v[250:251] op_sel_hi:[1,0]
	v_pk_mul_f32 v[140:141], v[78:79], v[250:251] op_sel_hi:[1,0]
	v_exp_f32_e32 v132, v132
	v_exp_f32_e32 v133, v133
	v_exp_f32_e32 v140, v140
	v_exp_f32_e32 v141, v141
	v_pk_add_f32 v[132:133], v[132:133], v[252:253] op_sel_hi:[1,0]
	v_pk_add_f32 v[140:141], v[140:141], v[252:253] op_sel_hi:[1,0]
	v_rcp_f32_e32 v132, v132
	v_rcp_f32_e32 v133, v133
	v_rcp_f32_e32 v140, v140
	v_rcp_f32_e32 v141, v141
	v_pk_mul_f32 v[76:77], v[76:77], v[132:133]
	v_pk_mul_f32 v[78:79], v[78:79], v[140:141]
	v_pk_mul_f32 v[76:77], v[76:77], v[72:73]
	v_pk_mul_f32 v[78:79], v[78:79], v[74:75]
	v_cvt_pk_bf16_f32 v94, v76, v77
	v_cvt_pk_bf16_f32 v95, v78, v79
	s_nop 1
	v_permlane16_swap_b32_e32 v93, v95
	v_permlane16_swap_b32_e32 v92, v94
	global_store_dwordx4 v247, v[92:95], s[66:67] offset:64
	v_pk_mul_f32 v[132:133], v[84:85], v[250:251] op_sel_hi:[1,0]
	v_pk_mul_f32 v[140:141], v[86:87], v[250:251] op_sel_hi:[1,0]
	v_exp_f32_e32 v132, v132
	v_exp_f32_e32 v133, v133
	v_exp_f32_e32 v140, v140
	v_exp_f32_e32 v141, v141
	v_pk_add_f32 v[132:133], v[132:133], v[252:253] op_sel_hi:[1,0]
	v_pk_add_f32 v[140:141], v[140:141], v[252:253] op_sel_hi:[1,0]
	v_rcp_f32_e32 v132, v132
	v_rcp_f32_e32 v133, v133
	v_rcp_f32_e32 v140, v140
	v_rcp_f32_e32 v141, v141
	v_pk_mul_f32 v[84:85], v[84:85], v[132:133]
	v_pk_mul_f32 v[86:87], v[86:87], v[140:141]
	v_pk_mul_f32 v[84:85], v[84:85], v[80:81]
	v_pk_mul_f32 v[86:87], v[86:87], v[82:83]
	v_cvt_pk_bf16_f32 v84, v84, v85
	v_cvt_pk_bf16_f32 v85, v86, v87
	v_pk_mul_f32 v[132:133], v[68:69], v[250:251] op_sel_hi:[1,0]
	v_pk_mul_f32 v[140:141], v[70:71], v[250:251] op_sel_hi:[1,0]
	v_exp_f32_e32 v132, v132
	v_exp_f32_e32 v133, v133
	v_exp_f32_e32 v140, v140
	v_exp_f32_e32 v141, v141
	v_pk_add_f32 v[132:133], v[132:133], v[252:253] op_sel_hi:[1,0]
	v_pk_add_f32 v[140:141], v[140:141], v[252:253] op_sel_hi:[1,0]
	v_rcp_f32_e32 v132, v132
	v_rcp_f32_e32 v133, v133
	v_rcp_f32_e32 v140, v140
	v_rcp_f32_e32 v141, v141
	v_pk_mul_f32 v[68:69], v[68:69], v[132:133]
	v_pk_mul_f32 v[70:71], v[70:71], v[140:141]
	v_pk_mul_f32 v[68:69], v[68:69], v[64:65]
	v_pk_mul_f32 v[70:71], v[70:71], v[66:67]
	v_cvt_pk_bf16_f32 v86, v68, v69
	v_cvt_pk_bf16_f32 v87, v70, v71
	s_nop 1
	v_permlane16_swap_b32_e32 v85, v87
	v_permlane16_swap_b32_e32 v84, v86
	global_store_dwordx4 v248, v[84:87], s[66:67] offset:64
	v_pk_mul_f32 v[132:133], v[60:61], v[250:251] op_sel_hi:[1,0]
	v_pk_mul_f32 v[140:141], v[62:63], v[250:251] op_sel_hi:[1,0]
	v_exp_f32_e32 v132, v132
	v_exp_f32_e32 v133, v133
	v_exp_f32_e32 v140, v140
	v_exp_f32_e32 v141, v141
	v_pk_add_f32 v[132:133], v[132:133], v[252:253] op_sel_hi:[1,0]
	v_pk_add_f32 v[140:141], v[140:141], v[252:253] op_sel_hi:[1,0]
	v_rcp_f32_e32 v132, v132
	v_rcp_f32_e32 v133, v133
	v_rcp_f32_e32 v140, v140
	v_rcp_f32_e32 v141, v141
	v_pk_mul_f32 v[60:61], v[60:61], v[132:133]
	v_pk_mul_f32 v[62:63], v[62:63], v[140:141]
	v_pk_mul_f32 v[60:61], v[60:61], v[56:57]
	v_pk_mul_f32 v[62:63], v[62:63], v[58:59]
	v_cvt_pk_bf16_f32 v60, v60, v61
	v_cvt_pk_bf16_f32 v61, v62, v63
	v_pk_mul_f32 v[132:133], v[44:45], v[250:251] op_sel_hi:[1,0]
	v_pk_mul_f32 v[140:141], v[46:47], v[250:251] op_sel_hi:[1,0]
	v_exp_f32_e32 v132, v132
	v_exp_f32_e32 v133, v133
	v_exp_f32_e32 v140, v140
	v_exp_f32_e32 v141, v141
	v_pk_add_f32 v[132:133], v[132:133], v[252:253] op_sel_hi:[1,0]
; __device__ __forceinline__ float siluf_(float x) { return x * __builtin_amdgcn_rcpf(1.f + __expf(-x)); }
;     ...
;     if (MODE == 4) {
;       u16* act = (u16*)(ws + OFF_RA);
;       uint2 opend4[2];
; #pragma unroll
;       for (int bj = 0; bj < 2; ++bj)
; #pragma unroll
;         for (int m = 0; m < 4; ++m)
; #pragma unroll
;           for (int n = 0; n < 2; ++n) {
;             int lane_i = lane_e;
;             asm volatile("" : "+v"(lane_i));
;             const int fr = lane_i & 15, fq = lane_i >> 4;
;             const int nc = tn * 128 + wr * 64 + m * 16 + fq * 4;
;             const int tok = bcol + bj * 128 + wc * 32 + n * 16 + fr;
;             f32x4 g = acc[0][bj][m][n], up = acc[1][bj][m][n];
;             uint2 o;
;             o.x = pk2(siluf_(g[0]) * up[0], siluf_(g[1]) * up[1]);
;             o.y = pk2(siluf_(g[2]) * up[2], siluf_(g[3]) * up[3]);
;             if ((m & 1) == 0) opend4[n] = o;
;             else {
;               const int ncw = tn * 128 + wr * 64 + ((m & ~1) + (fq & 1)) * 16 + (fq & ~1) * 4;
;               *(uint4*)(act + (size_t)tok * DFF + ncw) = swap_pair(opend4[n], o);
;             }
	v_pk_add_f32 v[140:141], v[140:141], v[252:253] op_sel_hi:[1,0]
	v_rcp_f32_e32 v132, v132
	v_rcp_f32_e32 v133, v133
	v_rcp_f32_e32 v140, v140
	v_rcp_f32_e32 v141, v141
	v_pk_mul_f32 v[44:45], v[44:45], v[132:133]
	v_pk_mul_f32 v[46:47], v[46:47], v[140:141]
	v_pk_mul_f32 v[44:45], v[44:45], v[40:41]
	v_pk_mul_f32 v[46:47], v[46:47], v[42:43]
	v_cvt_pk_bf16_f32 v62, v44, v45
	v_cvt_pk_bf16_f32 v63, v46, v47
	s_nop 1
	v_permlane16_swap_b32_e32 v61, v63
	v_permlane16_swap_b32_e32 v60, v62
	global_store_dwordx4 v249, v[60:63], s[66:67]
	v_pk_mul_f32 v[132:133], v[52:53], v[250:251] op_sel_hi:[1,0]
	v_pk_mul_f32 v[140:141], v[54:55], v[250:251] op_sel_hi:[1,0]
	v_exp_f32_e32 v132, v132
	v_exp_f32_e32 v133, v133
	v_exp_f32_e32 v140, v140
	v_exp_f32_e32 v141, v141
	v_pk_add_f32 v[132:133], v[132:133], v[252:253] op_sel_hi:[1,0]
	v_pk_add_f32 v[140:141], v[140:141], v[252:253] op_sel_hi:[1,0]
	v_rcp_f32_e32 v132, v132
	v_rcp_f32_e32 v133, v133
	v_rcp_f32_e32 v140, v140
	v_rcp_f32_e32 v141, v141
	v_pk_mul_f32 v[52:53], v[52:53], v[132:133]
	v_pk_mul_f32 v[54:55], v[54:55], v[140:141]
	v_pk_mul_f32 v[52:53], v[52:53], v[48:49]
	v_pk_mul_f32 v[54:55], v[54:55], v[50:51]
	v_cvt_pk_bf16_f32 v52, v52, v53
	v_cvt_pk_bf16_f32 v53, v54, v55
	v_pk_mul_f32 v[132:133], v[36:37], v[250:251] op_sel_hi:[1,0]
	v_pk_mul_f32 v[140:141], v[38:39], v[250:251] op_sel_hi:[1,0]
	v_exp_f32_e32 v132, v132
	v_exp_f32_e32 v133, v133
	v_exp_f32_e32 v140, v140
	v_exp_f32_e32 v141, v141
	v_pk_add_f32 v[132:133], v[132:133], v[252:253] op_sel_hi:[1,0]
	v_pk_add_f32 v[140:141], v[140:141], v[252:253] op_sel_hi:[1,0]
	v_rcp_f32_e32 v132, v132
	v_rcp_f32_e32 v133, v133
	v_rcp_f32_e32 v140, v140
	v_rcp_f32_e32 v141, v141
	v_pk_mul_f32 v[36:37], v[36:37], v[132:133]
	v_pk_mul_f32 v[38:39], v[38:39], v[140:141]
	v_pk_mul_f32 v[36:37], v[36:37], v[32:33]
	v_pk_mul_f32 v[38:39], v[38:39], v[34:35]
	v_cvt_pk_bf16_f32 v54, v36, v37
	v_cvt_pk_bf16_f32 v55, v38, v39
	s_nop 1
	v_permlane16_swap_b32_e32 v53, v55
	v_permlane16_swap_b32_e32 v52, v54
	global_store_dwordx4 v254, v[52:55], s[66:67]
	v_pk_mul_f32 v[132:133], v[28:29], v[250:251] op_sel_hi:[1,0]
	v_pk_mul_f32 v[140:141], v[30:31], v[250:251] op_sel_hi:[1,0]
	v_exp_f32_e32 v132, v132
	v_exp_f32_e32 v133, v133
	v_exp_f32_e32 v140, v140
	v_exp_f32_e32 v141, v141
	v_pk_add_f32 v[132:133], v[132:133], v[252:253] op_sel_hi:[1,0]
	v_pk_add_f32 v[140:141], v[140:141], v[252:253] op_sel_hi:[1,0]
	v_rcp_f32_e32 v132, v132
	v_rcp_f32_e32 v133, v133
	v_rcp_f32_e32 v140, v140
	v_rcp_f32_e32 v141, v141
	v_pk_mul_f32 v[28:29], v[28:29], v[132:133]
	v_pk_mul_f32 v[30:31], v[30:31], v[140:141]
	v_pk_mul_f32 v[28:29], v[28:29], v[24:25]
	v_pk_mul_f32 v[30:31], v[30:31], v[26:27]
	v_cvt_pk_bf16_f32 v28, v28, v29
	v_cvt_pk_bf16_f32 v29, v30, v31
	v_pk_mul_f32 v[132:133], v[12:13], v[250:251] op_sel_hi:[1,0]
	v_pk_mul_f32 v[140:141], v[14:15], v[250:251] op_sel_hi:[1,0]
	v_exp_f32_e32 v132, v132
	v_exp_f32_e32 v133, v133
	v_exp_f32_e32 v140, v140
	v_exp_f32_e32 v141, v141
	v_pk_add_f32 v[132:133], v[132:133], v[252:253] op_sel_hi:[1,0]
	v_pk_add_f32 v[140:141], v[140:141], v[252:253] op_sel_hi:[1,0]
	v_rcp_f32_e32 v132, v132
	v_rcp_f32_e32 v133, v133
	v_rcp_f32_e32 v140, v140
	v_rcp_f32_e32 v141, v141
	v_pk_mul_f32 v[12:13], v[12:13], v[132:133]
	v_pk_mul_f32 v[14:15], v[14:15], v[140:141]
	v_pk_mul_f32 v[12:13], v[12:13], v[8:9]
	v_pk_mul_f32 v[14:15], v[14:15], v[10:11]
	v_cvt_pk_bf16_f32 v30, v12, v13
	v_cvt_pk_bf16_f32 v31, v14, v15
	s_nop 1
	v_permlane16_swap_b32_e32 v29, v31
	v_permlane16_swap_b32_e32 v28, v30
	global_store_dwordx4 v249, v[28:31], s[66:67] offset:64
	v_pk_mul_f32 v[132:133], v[20:21], v[250:251] op_sel_hi:[1,0]
	v_pk_mul_f32 v[140:141], v[22:23], v[250:251] op_sel_hi:[1,0]
	v_exp_f32_e32 v132, v132
	v_exp_f32_e32 v133, v133
	v_exp_f32_e32 v140, v140
	v_exp_f32_e32 v141, v141
	v_pk_add_f32 v[132:133], v[132:133], v[252:253] op_sel_hi:[1,0]
	v_pk_add_f32 v[140:141], v[140:141], v[252:253] op_sel_hi:[1,0]
	v_rcp_f32_e32 v132, v132
	v_rcp_f32_e32 v133, v133
	v_rcp_f32_e32 v140, v140
	v_rcp_f32_e32 v141, v141
	v_pk_mul_f32 v[20:21], v[20:21], v[132:133]
	v_pk_mul_f32 v[22:23], v[22:23], v[140:141]
	v_pk_mul_f32 v[20:21], v[20:21], v[16:17]
	v_pk_mul_f32 v[22:23], v[22:23], v[18:19]
	v_cvt_pk_bf16_f32 v20, v20, v21
	v_cvt_pk_bf16_f32 v21, v22, v23
	v_pk_mul_f32 v[132:133], v[4:5], v[250:251] op_sel_hi:[1,0]
; __device__ __forceinline__ float siluf_(float x) { return x * __builtin_amdgcn_rcpf(1.f + __expf(-x)); }
;     ...
;   for (int u = vb; u < nunits; u += ustride) {
;     const int tm = u % nM, tn = u / nM + ((tn_skip >= 0 && u / nM >= tn_skip) ? 1 : 0);
;     const int brow = tn * 256, bcol = tm * 256;
;     const int un = u + ustride;
;     const bool has_next = un < nunits;
;     const int tn_n = un / nM + ((tn_skip >= 0 && un / nM >= tn_skip) ? 1 : 0);
;     const int brow_n = has_next ? tn_n * 256 : brow, bcol_n = has_next ? (un % nM) * 256 : bcol;
; #pragma unroll
;     for (int a = 0; a < 2; ++a)
; #pragma unroll
;       for (int b = 0; b < 2; ++b)
; #pragma unroll
;         for (int m = 0; m < 4; ++m)
; #pragma unroll
;           for (int n = 0; n < 2; ++n) acc[a][b][m][n] = f32x4{0.f, 0.f, 0.f, 0.f};
;     ...
;             o.x = pk2(siluf_(g[0]) * up[0], siluf_(g[1]) * up[1]);
;             o.y = pk2(siluf_(g[2]) * up[2], siluf_(g[3]) * up[3]);
;             if ((m & 1) == 0) opend4[n] = o;
;             else {
;               const int ncw = tn * 128 + wr * 64 + ((m & ~1) + (fq & 1)) * 16 + (fq & ~1) * 4;
;               *(uint4*)(act + (size_t)tok * DFF + ncw) = swap_pair(opend4[n], o);
;             }
	v_pk_mul_f32 v[140:141], v[6:7], v[250:251] op_sel_hi:[1,0]
	v_exp_f32_e32 v132, v132
	v_exp_f32_e32 v133, v133
	v_exp_f32_e32 v140, v140
	v_exp_f32_e32 v141, v141
	v_pk_add_f32 v[132:133], v[132:133], v[252:253] op_sel_hi:[1,0]
	v_pk_add_f32 v[140:141], v[140:141], v[252:253] op_sel_hi:[1,0]
	v_rcp_f32_e32 v132, v132
	v_rcp_f32_e32 v133, v133
	v_rcp_f32_e32 v140, v140
	v_rcp_f32_e32 v141, v141
	v_pk_mul_f32 v[4:5], v[4:5], v[132:133]
	v_pk_mul_f32 v[6:7], v[6:7], v[140:141]
	v_pk_mul_f32 v[4:5], v[4:5], v[0:1]
	v_pk_mul_f32 v[6:7], v[6:7], v[2:3]
	v_cvt_pk_bf16_f32 v22, v4, v5
	v_cvt_pk_bf16_f32 v23, v6, v7
	s_nop 1
	v_permlane16_swap_b32_e32 v21, v23
	v_permlane16_swap_b32_e32 v20, v22
	global_store_dwordx4 v254, v[20:23], s[66:67] offset:64
	s_nop 1
	v_mov_b32_e32 v0, 0
	v_mov_b32_e32 v1, v0
	v_mov_b32_e32 v2, v0
	v_mov_b32_e32 v3, v0
	v_mov_b32_e32 v8, v0
	v_mov_b32_e32 v9, v0
	v_mov_b32_e32 v10, v0
	v_mov_b32_e32 v11, v0
	v_mov_b32_e32 v16, v0
	v_mov_b32_e32 v17, v0
	v_mov_b32_e32 v18, v0
	v_mov_b32_e32 v19, v0
	v_mov_b32_e32 v24, v0
	v_mov_b32_e32 v25, v0
	v_mov_b32_e32 v26, v0
	v_mov_b32_e32 v27, v0
	v_mov_b32_e32 v32, v0
	v_mov_b32_e32 v33, v0
	v_mov_b32_e32 v34, v0
	v_mov_b32_e32 v35, v0
	v_mov_b32_e32 v40, v0
	v_mov_b32_e32 v41, v0
	v_mov_b32_e32 v42, v0
	v_mov_b32_e32 v43, v0
	v_mov_b32_e32 v48, v0
	v_mov_b32_e32 v49, v0
	v_mov_b32_e32 v50, v0
	v_mov_b32_e32 v51, v0
	v_mov_b32_e32 v56, v0
	v_mov_b32_e32 v57, v0
	v_mov_b32_e32 v58, v0
	v_mov_b32_e32 v59, v0
	v_mov_b32_e32 v64, v0
	v_mov_b32_e32 v65, v0
	v_mov_b32_e32 v66, v0
	v_mov_b32_e32 v67, v0
	v_mov_b32_e32 v72, v0
	v_mov_b32_e32 v73, v0
	v_mov_b32_e32 v74, v0
	v_mov_b32_e32 v75, v0
	v_mov_b32_e32 v80, v0
	v_mov_b32_e32 v81, v0
	v_mov_b32_e32 v82, v0
	v_mov_b32_e32 v83, v0
	v_mov_b32_e32 v88, v0
	v_mov_b32_e32 v89, v0
	v_mov_b32_e32 v90, v0
	v_mov_b32_e32 v91, v0
	v_mov_b32_e32 v96, v0
	v_mov_b32_e32 v97, v0
	v_mov_b32_e32 v98, v0
	v_mov_b32_e32 v99, v0
	v_mov_b32_e32 v104, v0
	v_mov_b32_e32 v105, v0
	v_mov_b32_e32 v106, v0
	v_mov_b32_e32 v107, v0
	v_mov_b32_e32 v112, v0
	v_mov_b32_e32 v113, v0
	v_mov_b32_e32 v114, v0
	v_mov_b32_e32 v115, v0
	v_mov_b32_e32 v120, v0
	v_mov_b32_e32 v121, v0
	v_mov_b32_e32 v122, v0
	v_mov_b32_e32 v123, v0
	v_mov_b32_e32 v4, v0
	v_mov_b32_e32 v5, v0
	v_mov_b32_e32 v6, v0
	v_mov_b32_e32 v7, v0
	v_mov_b32_e32 v12, v0
	v_mov_b32_e32 v13, v0
	v_mov_b32_e32 v14, v0
	v_mov_b32_e32 v15, v0
	v_mov_b32_e32 v20, v0
	v_mov_b32_e32 v21, v0
	v_mov_b32_e32 v22, v0
	v_mov_b32_e32 v23, v0
	v_mov_b32_e32 v28, v0
	v_mov_b32_e32 v29, v0
	v_mov_b32_e32 v30, v0
	v_mov_b32_e32 v31, v0
	v_mov_b32_e32 v36, v0
	v_mov_b32_e32 v37, v0
	v_mov_b32_e32 v38, v0
	v_mov_b32_e32 v39, v0
	v_mov_b32_e32 v44, v0
	v_mov_b32_e32 v45, v0
	v_mov_b32_e32 v46, v0
	v_mov_b32_e32 v47, v0
	v_mov_b32_e32 v52, v0
	v_mov_b32_e32 v53, v0
	v_mov_b32_e32 v54, v0
	v_mov_b32_e32 v55, v0
	v_mov_b32_e32 v60, v0
	v_mov_b32_e32 v61, v0
	v_mov_b32_e32 v62, v0
	v_mov_b32_e32 v63, v0
	v_mov_b32_e32 v68, v0
	v_mov_b32_e32 v69, v0
	v_mov_b32_e32 v70, v0
	v_mov_b32_e32 v71, v0
	v_mov_b32_e32 v76, v0
	v_mov_b32_e32 v77, v0
	v_mov_b32_e32 v78, v0
	v_mov_b32_e32 v79, v0
	v_mov_b32_e32 v84, v0
	v_mov_b32_e32 v85, v0
	v_mov_b32_e32 v86, v0
	v_mov_b32_e32 v87, v0
	v_mov_b32_e32 v92, v0
	v_mov_b32_e32 v93, v0
	v_mov_b32_e32 v94, v0
	v_mov_b32_e32 v95, v0
	v_mov_b32_e32 v100, v0
	v_mov_b32_e32 v101, v0
	v_mov_b32_e32 v102, v0
	v_mov_b32_e32 v103, v0
	v_mov_b32_e32 v108, v0
	v_mov_b32_e32 v109, v0
	v_mov_b32_e32 v110, v0
	v_mov_b32_e32 v111, v0
	v_mov_b32_e32 v116, v0
	v_mov_b32_e32 v117, v0
	v_mov_b32_e32 v118, v0
	v_mov_b32_e32 v119, v0
	v_mov_b32_e32 v124, v0
	v_mov_b32_e32 v125, v0
	v_mov_b32_e32 v126, v0
	v_mov_b32_e32 v127, v0
	s_and_b64 s[98:99], s[56:57], s[8:9]
	s_andn2_b64 vcc, exec, s[6:7]
	s_mov_b32 s1, s26
	s_cbranch_vccz .Lhm1009_x
	s_ashr_i32 s0, s1, 31
	s_lshr_b32 s0, s0, 26
	s_add_i32 s0, s1, s0
	s_ashr_i32 s28, s0, 6
	v_readlane_b32 s2, v244, 20
	s_lshl_b32 s0, s28, 8
	s_add_i32 s26, s1, s2
	s_cmpk_lt_i32 s26, 0xb00
	s_cselect_b64 s[8:9], -1, 0
	s_cmpk_gt_i32 s26, 0xaff
	s_cselect_b64 s[6:7], -1, 0
	s_and_b64 vcc, exec, s[6:7]
	s_mov_b32 s29, s0
	v_readlane_b32 s3, v244, 21
	s_cbranch_vccnz .Lhm1009_0
	s_ashr_i32 s2, s26, 31
	s_lshr_b32 s2, s2, 26
	s_add_i32 s2, s26, s2
	s_lshl_b32 s2, s2, 2
	s_and_b32 s29, s2, 0xffffff00

;     ...
;   for (int u = vb; u < nunits; u += ustride) {
;     const int tm = u % nM, tn = u / nM + ((tn_skip >= 0 && u / nM >= tn_skip) ? 1 : 0);
;     const int brow = tn * 256, bcol = tm * 256;
;     const int un = u + ustride;
;     const bool has_next = un < nunits;
;     const int tn_n = un / nM + ((tn_skip >= 0 && un / nM >= tn_skip) ? 1 : 0);
;     const int brow_n = has_next ? tn_n * 256 : brow, bcol_n = has_next ? (un % nM) * 256 : bcol;
;     ...
;     asm volatile("s_waitcnt vmcnt(0)" ::: "memory");
;     if (has_next && wr == 1) __builtin_amdgcn_s_barrier();
.Lhm1009_1:
	s_ashr_i32 s1, s0, 31
	s_lshl_b64 s[2:3], s[0:1], 12
	s_or_b32 s31, s0, 0x80
	s_or_b32 s34, s30, 0x80
	s_or_b32 s35, s27, 0x80
	s_or_b32 s36, s29, 0x80
	v_lshl_add_u64 v[132:133], v[130:131], 0, s[2:3]
	s_mov_b32 s1, 0
	s_waitcnt vmcnt(0)
	s_andn2_b64 vcc, exec, s[98:99]
	s_cbranch_vccnz .Lhm1009_k
	s_barrier
	s_branch .Lhm1009_k

; #define STAGE(P_, BASE, br, kt) do { const u16* _gb = (BASE) + (long)(br) * K + (long)(kt) * BK; \
;     _Pragma("unroll") for (int _i = 0; _i < 2; ++_i) { \
;       __builtin_amdgcn_global_load_lds((const unsigned*)(_gb + (long)_i * 64 * K + lane_off), \
;         (unsigned*)((char*)(P_) + lds_wbase + _i * 8192), 16, 0, 0); } } while (0)
; #define LDA(dst, b, h) _Pragma("unroll") for (int m = 0; m < 4; ++m) _Pragma("unroll") for (int k = 0; k < 2; ++k) \
;     dst[m][k] = *reinterpret_cast<const bf16x8*>((char*)SA(b, h) + lds_byte(wr * 64 + m * 16 + fr, k * 32 + fq * 8))
; #define LDB(dst, b, h) _Pragma("unroll") for (int n = 0; n < 2; ++n) _Pragma("unroll") for (int k = 0; k < 2; ++k) \
;     dst[n][k] = *reinterpret_cast<const bf16x8*>((char*)SB(b, h) + lds_byte(wc * 32 + n * 16 + fr, k * 32 + fq * 8))
; #define MMA(ai, bj, At_, Bt_) do { __builtin_amdgcn_s_setprio(1); \
;     _Pragma("unroll") for (int m = 0; m < 4; ++m) _Pragma("unroll") for (int n = 0; n < 2; ++n) _Pragma("unroll") for (int k = 0; k < 2; ++k) \
;       acc[ai][bj][m][n] = __builtin_amdgcn_mfma_f32_16x16x32_bf16(At_[m][k], Bt_[n][k], acc[ai][bj][m][n], 0, 0, 0); \
;     __builtin_amdgcn_s_setprio(0); } while (0)
; #define WAIT_V(n) asm volatile("s_waitcnt vmcnt(" #n ")" ::: "memory")
; #define BAR __builtin_amdgcn_s_barrier()
; template <int PRE> ...
;     ...
;   for (int t = 0; t < nt; t += 2) {
;     LDB(B0, 0, 0); SCHED; LDA(At, 0, 0); STAGE(SA(1, 1), A, brow + HALF, t + 1);
;     WAIT_L(8); BAR; WAIT_L(0); MMA(0, 0, At, B0); BAR; SCHED;
;     LDB(B1, 0, 1); STAGEW(SB(0, 0), Bt, bcol, bcol_n, t + 2);
;     BAR; WAIT_L(0); MMA(0, 1, At, B1); BAR;
;     LDA(At, 0, 1); STAGEW(SA(0, 0), A, brow, brow_n, t + 2);
;     BAR; WAIT_L(0); MMA(1, 0, At, B0); BAR; SCHED;
;     STAGEW(SB(0, 1), Bt, bcol + HALF, bcol_n + HALF, t + 2);
;     WAIT_V(6); BAR; MMA(1, 1, At, B1); BAR;
;     LDB(B0, 1, 0); SCHED; LDA(At, 1, 0); STAGEW(SA(0, 1), A, brow + HALF, brow_n + HALF, t + 2);
;     WAIT_L(8); BAR; WAIT_L(0); MMA(0, 0, At, B0); BAR; SCHED;
;     LDB(B1, 1, 1); STAGEW(SB(1, 0), Bt, bcol, bcol_n, t + 3);
;     BAR; WAIT_L(0); MMA(0, 1, At, B1); BAR;
;     LDA(At, 1, 1); STAGEW(SA(1, 0), A, brow, brow_n, t + 3);
;     BAR; WAIT_L(0); MMA(1, 0, At, B0); BAR; SCHED;
;     STAGEW(SB(1, 1), Bt, bcol + HALF, bcol_n + HALF, t + 3);
;     WAIT_V(6); BAR; MMA(1, 1, At, B1); BAR;
;   }
.Lhm1077_k:
.LBB0_1083:
	v_add_u32_e32 v142, s81, v151
	ds_read_b128 v[134:137], v142
	ds_read_b128 v[138:141], v142 offset:1024
	ds_read_b128 v[146:149], v142 offset:2048
	ds_read_b128 v[156:159], v142 offset:3072
	s_add_i32 m0, s2, 0xc000
	ds_read_b128 v[160:163], v144
	ds_read_b128 v[168:171], v144 offset:1024
	ds_read_b128 v[172:175], v152
	ds_read_b128 v[176:179], v152 offset:1024
	ds_read_b128 v[180:183], v153
	ds_read_b128 v[184:187], v153 offset:1024
	ds_read_b128 v[188:191], v154
	ds_read_b128 v[192:195], v154 offset:1024
	global_load_lds_dwordx4 v[128:129], off
	v_lshl_add_u64 v[142:143], v[128:129], 0, s[40:41]
	s_add_i32 m0, s2, 0xe000
	s_nop 0
	global_load_lds_dwordx4 v[142:143], off
	s_waitcnt lgkmcnt(8)
	s_barrier
	s_waitcnt lgkmcnt(0)
	v_mfma_f32_16x16x32_bf16 v[124:127], v[160:163], v[134:137], v[124:127]
	v_mfma_f32_16x16x32_bf16 v[120:123], v[160:163], v[146:149], v[120:123]
	v_mfma_f32_16x16x32_bf16 v[116:119], v[172:175], v[134:137], v[116:119]
	v_mfma_f32_16x16x32_bf16 v[112:115], v[172:175], v[146:149], v[112:115]
	v_mfma_f32_16x16x32_bf16 v[108:111], v[180:183], v[134:137], v[108:111]
	v_mfma_f32_16x16x32_bf16 v[104:107], v[180:183], v[146:149], v[104:107]
	v_mfma_f32_16x16x32_bf16 v[100:103], v[188:191], v[134:137], v[100:103]
	v_mfma_f32_16x16x32_bf16 v[96:99], v[188:191], v[146:149], v[96:99]
	v_mfma_f32_16x16x32_bf16 v[124:127], v[168:171], v[138:141], v[124:127]
	v_mfma_f32_16x16x32_bf16 v[120:123], v[168:171], v[156:159], v[120:123]
	v_mfma_f32_16x16x32_bf16 v[116:119], v[176:179], v[138:141], v[116:119]
	v_mfma_f32_16x16x32_bf16 v[112:115], v[176:179], v[156:159], v[112:115]
	v_mfma_f32_16x16x32_bf16 v[108:111], v[184:187], v[138:141], v[108:111]
	v_mfma_f32_16x16x32_bf16 v[104:107], v[184:187], v[156:159], v[104:107]
	v_mfma_f32_16x16x32_bf16 v[100:103], v[192:195], v[138:141], v[100:103]
	v_mfma_f32_16x16x32_bf16 v[96:99], v[192:195], v[156:159], v[96:99]
	s_barrier
	s_add_i32 s34, s31, 2
	s_cmpk_lt_u32 s31, 0x56
	s_cselect_b64 s[0:1], -1, 0
	s_and_b64 vcc, s[0:1], exec
	s_cselect_b32 s0, s24, s26
	s_mulk_i32 s0, 0x1600
	s_cselect_b32 s18, 0, 0xffffffa8
	s_cselect_b32 s35, s23, s25
	s_cselect_b32 s38, s29, s28
	s_cselect_b32 s39, s27, s30
	s_ashr_i32 s1, s0, 31
	s_lshl_b64 s[0:1], s[0:1], 1
	s_add_u32 s36, s66, s0
	s_addc_u32 s37, s67, s1
	s_add_i32 s18, s34, s18
	s_lshl_b64 s[0:1], s[18:19], 7
	s_add_u32 s36, s36, s0
	v_add_u32_e32 v142, s82, v151
	s_addc_u32 s37, s37, s1
	s_mov_b32 m0, s3
	ds_read_b128 v[210:213], v142
	ds_read_b128 v[214:217], v142 offset:1024
	ds_read_b128 v[218:221], v142 offset:2048
	ds_read_b128 v[222:225], v142 offset:3072
	v_lshl_add_u64 v[142:143], s[36:37], 0, v[130:131]
	global_load_lds_dwordx4 v[142:143], off
	v_lshl_add_u64 v[142:143], v[142:143], 0, s[40:41]
	s_mov_b32 m0, s4
	s_nop 0
	global_load_lds_dwordx4 v[142:143], off
	s_barrier
	s_waitcnt lgkmcnt(0)
	v_mfma_f32_16x16x32_bf16 v[92:95], v[160:163], v[210:213], v[92:95]
	v_mfma_f32_16x16x32_bf16 v[88:91], v[160:163], v[218:221], v[88:91]
	v_mfma_f32_16x16x32_bf16 v[84:87], v[172:175], v[210:213], v[84:87]
	v_mfma_f32_16x16x32_bf16 v[80:83], v[172:175], v[218:221], v[80:83]
	v_mfma_f32_16x16x32_bf16 v[76:79], v[180:183], v[210:213], v[76:79]
	v_mfma_f32_16x16x32_bf16 v[72:75], v[180:183], v[218:221], v[72:75]
	v_mfma_f32_16x16x32_bf16 v[68:71], v[188:191], v[210:213], v[68:71]
	v_mfma_f32_16x16x32_bf16 v[64:67], v[188:191], v[218:221], v[64:67]
	v_mfma_f32_16x16x32_bf16 v[92:95], v[168:171], v[214:217], v[92:95]
	v_mfma_f32_16x16x32_bf16 v[88:91], v[168:171], v[222:225], v[88:91]
	v_mfma_f32_16x16x32_bf16 v[84:87], v[176:179], v[214:217], v[84:87]
	v_mfma_f32_16x16x32_bf16 v[80:83], v[176:179], v[222:225], v[80:83]
	v_mfma_f32_16x16x32_bf16 v[76:79], v[184:187], v[214:217], v[76:79]
	v_mfma_f32_16x16x32_bf16 v[72:75], v[184:187], v[222:225], v[72:75]
	v_mfma_f32_16x16x32_bf16 v[68:71], v[192:195], v[214:217], v[68:71]
	v_mfma_f32_16x16x32_bf16 v[64:67], v[192:195], v[222:225], v[64:67]
	s_mul_hi_i32 s18, s35, 0x2c00
	s_mulk_i32 s35, 0x2c00
	s_add_u32 s35, s79, s35
	s_addc_u32 s18, s80, s18
	s_add_u32 s36, s35, s0
	s_addc_u32 s37, s18, s1
	s_mov_b32 m0, s2
	v_lshl_add_u64 v[142:143], s[36:37], 0, v[130:131]
	s_barrier
	ds_read_b128 v[160:163], v144 offset:16384
	ds_read_b128 v[168:171], v144 offset:17408
	ds_read_b128 v[172:175], v152 offset:16384
	ds_read_b128 v[176:179], v152 offset:17408
	ds_read_b128 v[180:183], v153 offset:16384
	ds_read_b128 v[184:187], v153 offset:17408
	ds_read_b128 v[188:191], v154 offset:16384
	ds_read_b128 v[192:195], v154 offset:17408
	global_load_lds_dwordx4 v[142:143], off
	v_lshl_add_u64 v[142:143], v[142:143], 0, s[40:41]
	s_mov_b32 m0, s5
	s_nop 0
	global_load_lds_dwordx4 v[142:143], off
	s_barrier
	s_waitcnt lgkmcnt(0)
	v_mfma_f32_16x16x32_bf16 v[60:63], v[160:163], v[134:137], v[60:63]
	v_mfma_f32_16x16x32_bf16 v[56:59], v[160:163], v[146:149], v[56:59]
	v_mfma_f32_16x16x32_bf16 v[52:55], v[172:175], v[134:137], v[52:55]
	v_mfma_f32_16x16x32_bf16 v[48:51], v[172:175], v[146:149], v[48:51]
	v_mfma_f32_16x16x32_bf16 v[44:47], v[180:183], v[134:137], v[44:47]
	v_mfma_f32_16x16x32_bf16 v[40:43], v[180:183], v[146:149], v[40:43]
	v_mfma_f32_16x16x32_bf16 v[36:39], v[188:191], v[134:137], v[36:39]
	v_mfma_f32_16x16x32_bf16 v[32:35], v[188:191], v[146:149], v[32:35]
	v_mfma_f32_16x16x32_bf16 v[60:63], v[168:171], v[138:141], v[60:63]
	v_mfma_f32_16x16x32_bf16 v[56:59], v[168:171], v[156:159], v[56:59]
	v_mfma_f32_16x16x32_bf16 v[52:55], v[176:179], v[138:141], v[52:55]
	v_mfma_f32_16x16x32_bf16 v[48:51], v[176:179], v[156:159], v[48:51]
	v_mfma_f32_16x16x32_bf16 v[44:47], v[184:187], v[138:141], v[44:47]
	v_mfma_f32_16x16x32_bf16 v[40:43], v[184:187], v[156:159], v[40:43]
	v_mfma_f32_16x16x32_bf16 v[36:39], v[192:195], v[138:141], v[36:39]
	v_mfma_f32_16x16x32_bf16 v[32:35], v[192:195], v[156:159], v[32:35]
	s_barrier
; #define STAGE(P_, BASE, br, kt) do { const u16* _gb = (BASE) + (long)(br) * K + (long)(kt) * BK; \
;     _Pragma("unroll") for (int _i = 0; _i < 2; ++_i) { \
;       __builtin_amdgcn_global_load_lds((const unsigned*)(_gb + (long)_i * 64 * K + lane_off), \
;         (unsigned*)((char*)(P_) + lds_wbase + _i * 8192), 16, 0, 0); } } while (0)
; #define LDA(dst, b, h) _Pragma("unroll") for (int m = 0; m < 4; ++m) _Pragma("unroll") for (int k = 0; k < 2; ++k) \
;     dst[m][k] = *reinterpret_cast<const bf16x8*>((char*)SA(b, h) + lds_byte(wr * 64 + m * 16 + fr, k * 32 + fq * 8))
; #define LDB(dst, b, h) _Pragma("unroll") for (int n = 0; n < 2; ++n) _Pragma("unroll") for (int k = 0; k < 2; ++k) \
;     dst[n][k] = *reinterpret_cast<const bf16x8*>((char*)SB(b, h) + lds_byte(wc * 32 + n * 16 + fr, k * 32 + fq * 8))
; #define MMA(ai, bj, At_, Bt_) do { __builtin_amdgcn_s_setprio(1); \
;     _Pragma("unroll") for (int m = 0; m < 4; ++m) _Pragma("unroll") for (int n = 0; n < 2; ++n) _Pragma("unroll") for (int k = 0; k < 2; ++k) \
;       acc[ai][bj][m][n] = __builtin_amdgcn_mfma_f32_16x16x32_bf16(At_[m][k], Bt_[n][k], acc[ai][bj][m][n], 0, 0, 0); \
;     __builtin_amdgcn_s_setprio(0); } while (0)
; #define WAIT_V(n) asm volatile("s_waitcnt vmcnt(" #n ")" ::: "memory")
; #define BAR __builtin_amdgcn_s_barrier()
; template <int PRE> ...
;     ...
;   for (int t = 0; t < nt; t += 2) {
;     LDB(B0, 0, 0); SCHED; LDA(At, 0, 0); STAGE(SA(1, 1), A, brow + HALF, t + 1);
;     WAIT_L(8); BAR; WAIT_L(0); MMA(0, 0, At, B0); BAR; SCHED;
;     LDB(B1, 0, 1); STAGEW(SB(0, 0), Bt, bcol, bcol_n, t + 2);
;     BAR; WAIT_L(0); MMA(0, 1, At, B1); BAR;
;     LDA(At, 0, 1); STAGEW(SA(0, 0), A, brow, brow_n, t + 2);
;     BAR; WAIT_L(0); MMA(1, 0, At, B0); BAR; SCHED;
;     STAGEW(SB(0, 1), Bt, bcol + HALF, bcol_n + HALF, t + 2);
;     WAIT_V(6); BAR; MMA(1, 1, At, B1); BAR;
;     LDB(B0, 1, 0); SCHED; LDA(At, 1, 0); STAGEW(SA(0, 1), A, brow + HALF, brow_n + HALF, t + 2);
;     WAIT_L(8); BAR; WAIT_L(0); MMA(0, 0, At, B0); BAR; SCHED;
;     LDB(B1, 1, 1); STAGEW(SB(1, 0), Bt, bcol, bcol_n, t + 3);
;     BAR; WAIT_L(0); MMA(0, 1, At, B1); BAR;
;     LDA(At, 1, 1); STAGEW(SA(1, 0), A, brow, brow_n, t + 3);
;     BAR; WAIT_L(0); MMA(1, 0, At, B0); BAR; SCHED;
;     STAGEW(SB(1, 1), Bt, bcol + HALF, bcol_n + HALF, t + 3);
;     WAIT_V(6); BAR; MMA(1, 1, At, B1); BAR;
;   }
	s_mul_i32 s36, s38, 0x1600
	s_ashr_i32 s37, s36, 31
	s_lshl_b64 s[36:37], s[36:37], 1
	s_add_u32 s18, s66, s36
	s_addc_u32 s35, s67, s37
	s_add_u32 s36, s18, s0
	s_addc_u32 s37, s35, s1
	s_mov_b32 m0, s10
	v_lshl_add_u64 v[134:135], s[36:37], 0, v[130:131]
	global_load_lds_dwordx4 v[134:135], off
	v_lshl_add_u64 v[134:135], v[134:135], 0, s[40:41]
	s_mov_b32 m0, s11
	s_nop 0
	global_load_lds_dwordx4 v[134:135], off
	s_waitcnt vmcnt(6)
	s_barrier
	v_mfma_f32_16x16x32_bf16 v[28:31], v[160:163], v[210:213], v[28:31]
	v_mfma_f32_16x16x32_bf16 v[24:27], v[160:163], v[218:221], v[24:27]
	v_mfma_f32_16x16x32_bf16 v[20:23], v[172:175], v[210:213], v[20:23]
	v_mfma_f32_16x16x32_bf16 v[16:19], v[172:175], v[218:221], v[16:19]
	v_mfma_f32_16x16x32_bf16 v[12:15], v[180:183], v[210:213], v[12:15]
	v_mfma_f32_16x16x32_bf16 v[8:11], v[180:183], v[218:221], v[8:11]
	v_mfma_f32_16x16x32_bf16 v[4:7], v[188:191], v[210:213], v[4:7]
	v_mfma_f32_16x16x32_bf16 v[0:3], v[188:191], v[218:221], v[0:3]
	v_mfma_f32_16x16x32_bf16 v[28:31], v[168:171], v[214:217], v[28:31]
	v_mfma_f32_16x16x32_bf16 v[24:27], v[168:171], v[222:225], v[24:27]
	v_mfma_f32_16x16x32_bf16 v[20:23], v[176:179], v[214:217], v[20:23]
	v_mfma_f32_16x16x32_bf16 v[16:19], v[176:179], v[222:225], v[16:19]
	v_mfma_f32_16x16x32_bf16 v[12:15], v[184:187], v[214:217], v[12:15]
	v_mfma_f32_16x16x32_bf16 v[8:11], v[184:187], v[222:225], v[8:11]
	v_mfma_f32_16x16x32_bf16 v[4:7], v[192:195], v[214:217], v[4:7]
	v_mfma_f32_16x16x32_bf16 v[0:3], v[192:195], v[222:225], v[0:3]
	v_add_u32_e32 v142, s83, v151
	s_barrier
	ds_read_b128 v[134:137], v142
	ds_read_b128 v[138:141], v142 offset:1024
	ds_read_b128 v[146:149], v142 offset:2048
	ds_read_b128 v[156:159], v142 offset:3072
	s_mul_hi_i32 s18, s39, 0x2c00
	s_mulk_i32 s39, 0x2c00
	s_add_u32 s35, s79, s39
	s_addc_u32 s18, s80, s18
	s_add_u32 s0, s35, s0
	s_addc_u32 s1, s18, s1
	s_mov_b32 m0, s12
	v_lshl_add_u64 v[142:143], s[0:1], 0, v[130:131]
	ds_read_b128 v[160:163], v144 offset:32768
	ds_read_b128 v[168:171], v144 offset:33792
	ds_read_b128 v[172:175], v152 offset:32768
	ds_read_b128 v[176:179], v152 offset:33792
	ds_read_b128 v[180:183], v153 offset:32768
	ds_read_b128 v[184:187], v153 offset:33792
	ds_read_b128 v[188:191], v154 offset:32768
	ds_read_b128 v[192:195], v154 offset:33792
	global_load_lds_dwordx4 v[142:143], off
	v_lshl_add_u64 v[142:143], v[142:143], 0, s[40:41]
	s_mov_b32 m0, s13
	s_nop 0
	global_load_lds_dwordx4 v[142:143], off
	s_waitcnt lgkmcnt(8)
	s_barrier
	s_waitcnt lgkmcnt(0)
	v_mfma_f32_16x16x32_bf16 v[124:127], v[160:163], v[134:137], v[124:127]
	v_mfma_f32_16x16x32_bf16 v[120:123], v[160:163], v[146:149], v[120:123]
	v_mfma_f32_16x16x32_bf16 v[116:119], v[172:175], v[134:137], v[116:119]
	v_mfma_f32_16x16x32_bf16 v[112:115], v[172:175], v[146:149], v[112:115]
	v_mfma_f32_16x16x32_bf16 v[108:111], v[180:183], v[134:137], v[108:111]
	v_mfma_f32_16x16x32_bf16 v[104:107], v[180:183], v[146:149], v[104:107]
	v_mfma_f32_16x16x32_bf16 v[100:103], v[188:191], v[134:137], v[100:103]
	v_mfma_f32_16x16x32_bf16 v[96:99], v[188:191], v[146:149], v[96:99]
	v_mfma_f32_16x16x32_bf16 v[124:127], v[168:171], v[138:141], v[124:127]
	v_mfma_f32_16x16x32_bf16 v[120:123], v[168:171], v[156:159], v[120:123]
	v_mfma_f32_16x16x32_bf16 v[116:119], v[176:179], v[138:141], v[116:119]
	v_mfma_f32_16x16x32_bf16 v[112:115], v[176:179], v[156:159], v[112:115]
	v_mfma_f32_16x16x32_bf16 v[108:111], v[184:187], v[138:141], v[108:111]
	v_mfma_f32_16x16x32_bf16 v[104:107], v[184:187], v[156:159], v[104:107]
	v_mfma_f32_16x16x32_bf16 v[100:103], v[192:195], v[138:141], v[100:103]
	v_mfma_f32_16x16x32_bf16 v[96:99], v[192:195], v[156:159], v[96:99]
	s_barrier
	s_cmpk_lt_u32 s31, 0x55
	s_cselect_b32 s0, s24, s26
	s_mulk_i32 s0, 0x1600
	s_cselect_b32 s18, 0, 0xffffffa8
	s_cselect_b32 s35, s23, s25
	s_cselect_b32 s38, s29, s28
	s_ashr_i32 s1, s0, 31
	s_lshl_b64 s[0:1], s[0:1], 1
	s_add_u32 s36, s66, s0
	s_addc_u32 s37, s67, s1
	s_add_i32 s0, s18, s31
	s_add_i32 s18, s0, 3
	s_lshl_b64 s[0:1], s[18:19], 7
	s_add_u32 s36, s36, s0
	v_add_u32_e32 v142, s84, v151
	s_addc_u32 s37, s37, s1
	s_mov_b32 m0, s14
	ds_read_b128 v[210:213], v142
	ds_read_b128 v[214:217], v142 offset:1024
	ds_read_b128 v[218:221], v142 offset:2048
	ds_read_b128 v[222:225], v142 offset:3072
	v_lshl_add_u64 v[142:143], s[36:37], 0, v[130:131]
	global_load_lds_dwordx4 v[142:143], off
	v_lshl_add_u64 v[142:143], v[142:143], 0, s[40:41]
	s_mov_b32 m0, s15
	s_nop 0
	global_load_lds_dwordx4 v[142:143], off
	s_barrier
	s_waitcnt lgkmcnt(0)
	v_mfma_f32_16x16x32_bf16 v[92:95], v[160:163], v[210:213], v[92:95]
	v_mfma_f32_16x16x32_bf16 v[88:91], v[160:163], v[218:221], v[88:91]
	v_mfma_f32_16x16x32_bf16 v[84:87], v[172:175], v[210:213], v[84:87]
	v_mfma_f32_16x16x32_bf16 v[80:83], v[172:175], v[218:221], v[80:83]
	v_mfma_f32_16x16x32_bf16 v[76:79], v[180:183], v[210:213], v[76:79]
	v_mfma_f32_16x16x32_bf16 v[72:75], v[180:183], v[218:221], v[72:75]
	v_mfma_f32_16x16x32_bf16 v[68:71], v[188:191], v[210:213], v[68:71]
	v_mfma_f32_16x16x32_bf16 v[64:67], v[188:191], v[218:221], v[64:67]
	v_mfma_f32_16x16x32_bf16 v[92:95], v[168:171], v[214:217], v[92:95]
	v_mfma_f32_16x16x32_bf16 v[88:91], v[168:171], v[222:225], v[88:91]
	v_mfma_f32_16x16x32_bf16 v[84:87], v[176:179], v[214:217], v[84:87]
	v_mfma_f32_16x16x32_bf16 v[80:83], v[176:179], v[222:225], v[80:83]
	v_mfma_f32_16x16x32_bf16 v[76:79], v[184:187], v[214:217], v[76:79]
	v_mfma_f32_16x16x32_bf16 v[72:75], v[184:187], v[222:225], v[72:75]
	v_mfma_f32_16x16x32_bf16 v[68:71], v[192:195], v[214:217], v[68:71]
	v_mfma_f32_16x16x32_bf16 v[64:67], v[192:195], v[222:225], v[64:67]
	s_mul_hi_i32 s18, s35, 0x2c00
	s_mulk_i32 s35, 0x2c00
	s_add_u32 s31, s79, s35
	s_addc_u32 s18, s80, s18
	s_add_u32 s36, s31, s0
	s_addc_u32 s37, s18, s1
	s_mov_b32 m0, s16
	v_lshl_add_u64 v[142:143], s[36:37], 0, v[130:131]
	s_barrier
; __device__ __forceinline__ float bflo(unsigned u) { return __uint_as_float(u << 16); }
; __device__ __forceinline__ float bfhi(unsigned u) { return __uint_as_float(u & 0xffff0000u); }
; #define MMA(ai, bj, At_, Bt_) do { __builtin_amdgcn_s_setprio(1); \
;     _Pragma("unroll") for (int m = 0; m < 4; ++m) _Pragma("unroll") for (int n = 0; n < 2; ++n) _Pragma("unroll") for (int k = 0; k < 2; ++k) \
;       acc[ai][bj][m][n] = __builtin_amdgcn_mfma_f32_16x16x32_bf16(At_[m][k], Bt_[n][k], acc[ai][bj][m][n], 0, 0, 0); \
;     __builtin_amdgcn_s_setprio(0); } while (0)
; #define WAIT_V(n) asm volatile("s_waitcnt vmcnt(" #n ")" ::: "memory")
; #define WAIT_L(n) asm volatile("s_waitcnt lgkmcnt(" #n ")" ::: "memory")
; #define BAR __builtin_amdgcn_s_barrier()
; #define SCHED __builtin_amdgcn_sched_barrier(0)
; #define STAGEW(P_, BASE, cur, nxt, kt_) do { const bool _wr = (kt_) >= nt; \
;     STAGE(P_, BASE, (_wr ? (nxt) : (cur)), (_wr ? (kt_) - nt : (kt_))); } while (0)
; #define WIDE_STORE(BASE, LD, COFF, O) do { if ((m & 1) == 0) opend[n] = (O); \
;                 else *(uint4*)((BASE) + (size_t)tok * (LD) + (ncw - (COFF))) = swap_pair(opend[n], (O)); } while (0)
; template <int PRE> ...
;     ...
;     BAR; WAIT_L(0); MMA(1, 0, At, B0); BAR; SCHED;
;     STAGEW(SB(1, 1), Bt, bcol + HALF, bcol_n + HALF, t + 3);
;     WAIT_V(6); BAR; MMA(1, 1, At, B1); BAR;
;   }
;   if (wr == 0) BAR;
;     ...
;               } else {
;                 uint2* ph = (uint2*)((u16*)(ws + OFF_RB) + (size_t)tok * DM + nc);
;                 const uint2 hb = *ph;
;                 uint2 o; o.x = pk2(bflo(hb.x) + v[0], bfhi(hb.x) + v[1]); o.y = pk2(bflo(hb.y) + v[2], bfhi(hb.y) + v[3]);
;                 WIDE_STORE((u16*)(ws + OFF_RB), DM, 0, o);
	ds_read_b128 v[160:163], v144 offset:49152
	ds_read_b128 v[168:171], v144 offset:50176
	ds_read_b128 v[172:175], v152 offset:49152
	ds_read_b128 v[176:179], v152 offset:50176
	ds_read_b128 v[180:183], v153 offset:49152
	ds_read_b128 v[184:187], v153 offset:50176
	ds_read_b128 v[188:191], v154 offset:49152
	ds_read_b128 v[192:195], v154 offset:50176
	global_load_lds_dwordx4 v[142:143], off
	v_lshl_add_u64 v[142:143], v[142:143], 0, s[40:41]
	s_mov_b32 m0, s17
	s_nop 0
	global_load_lds_dwordx4 v[142:143], off
	s_barrier
	s_waitcnt lgkmcnt(0)
	v_mfma_f32_16x16x32_bf16 v[60:63], v[160:163], v[134:137], v[60:63]
	v_mfma_f32_16x16x32_bf16 v[56:59], v[160:163], v[146:149], v[56:59]
	v_mfma_f32_16x16x32_bf16 v[52:55], v[172:175], v[134:137], v[52:55]
	v_mfma_f32_16x16x32_bf16 v[48:51], v[172:175], v[146:149], v[48:51]
	v_mfma_f32_16x16x32_bf16 v[44:47], v[180:183], v[134:137], v[44:47]
	v_mfma_f32_16x16x32_bf16 v[40:43], v[180:183], v[146:149], v[40:43]
	v_mfma_f32_16x16x32_bf16 v[36:39], v[188:191], v[134:137], v[36:39]
	v_mfma_f32_16x16x32_bf16 v[32:35], v[188:191], v[146:149], v[32:35]
	v_mfma_f32_16x16x32_bf16 v[60:63], v[168:171], v[138:141], v[60:63]
	v_mfma_f32_16x16x32_bf16 v[56:59], v[168:171], v[156:159], v[56:59]
	v_mfma_f32_16x16x32_bf16 v[52:55], v[176:179], v[138:141], v[52:55]
	v_mfma_f32_16x16x32_bf16 v[48:51], v[176:179], v[156:159], v[48:51]
	v_mfma_f32_16x16x32_bf16 v[44:47], v[184:187], v[138:141], v[44:47]
	v_mfma_f32_16x16x32_bf16 v[40:43], v[184:187], v[156:159], v[40:43]
	v_mfma_f32_16x16x32_bf16 v[36:39], v[192:195], v[138:141], v[36:39]
	v_mfma_f32_16x16x32_bf16 v[32:35], v[192:195], v[156:159], v[32:35]
	s_barrier
	s_mul_i32 s36, s38, 0x1600
	s_ashr_i32 s37, s36, 31
	s_lshl_b64 s[36:37], s[36:37], 1
	s_add_u32 s18, s66, s36
	s_addc_u32 s31, s67, s37
	s_add_u32 s0, s18, s0
	s_addc_u32 s1, s31, s1
	s_mov_b32 m0, s20
	v_lshl_add_u64 v[134:135], s[0:1], 0, v[130:131]
	global_load_lds_dwordx4 v[134:135], off
	v_lshl_add_u64 v[134:135], v[134:135], 0, s[40:41]
	s_mov_b32 m0, s21
	s_nop 0
	global_load_lds_dwordx4 v[134:135], off
	s_waitcnt vmcnt(6)
	s_barrier
	v_mfma_f32_16x16x32_bf16 v[28:31], v[160:163], v[210:213], v[28:31]
	v_mfma_f32_16x16x32_bf16 v[24:27], v[160:163], v[218:221], v[24:27]
	v_mfma_f32_16x16x32_bf16 v[20:23], v[172:175], v[210:213], v[20:23]
	v_mfma_f32_16x16x32_bf16 v[16:19], v[172:175], v[218:221], v[16:19]
	v_mfma_f32_16x16x32_bf16 v[12:15], v[180:183], v[210:213], v[12:15]
	v_mfma_f32_16x16x32_bf16 v[8:11], v[180:183], v[218:221], v[8:11]
	v_mfma_f32_16x16x32_bf16 v[4:7], v[188:191], v[210:213], v[4:7]
	v_mfma_f32_16x16x32_bf16 v[0:3], v[188:191], v[218:221], v[0:3]
	v_mfma_f32_16x16x32_bf16 v[28:31], v[168:171], v[214:217], v[28:31]
	v_mfma_f32_16x16x32_bf16 v[24:27], v[168:171], v[222:225], v[24:27]
	v_mfma_f32_16x16x32_bf16 v[20:23], v[176:179], v[214:217], v[20:23]
	v_mfma_f32_16x16x32_bf16 v[16:19], v[176:179], v[222:225], v[16:19]
	v_mfma_f32_16x16x32_bf16 v[12:15], v[184:187], v[214:217], v[12:15]
	v_mfma_f32_16x16x32_bf16 v[8:11], v[184:187], v[222:225], v[8:11]
	v_mfma_f32_16x16x32_bf16 v[4:7], v[192:195], v[214:217], v[4:7]
	v_mfma_f32_16x16x32_bf16 v[0:3], v[192:195], v[222:225], v[0:3]
	v_lshl_add_u64 v[128:129], v[128:129], 0, s[46:47]
	s_mov_b32 s31, s34
	s_barrier
	s_cbranch_vccnz .LBB0_1083
	s_andn2_b64 vcc, exec, s[58:59]
	s_cbranch_vccnz .LBB0_1086
	s_barrier
.LBB0_1086:
	v_readlane_b32 s26, v245, 25
	v_readlane_b32 s27, v245, 26
	v_readlane_b32 s34, v243, 2
	v_readlane_b32 s31, v244, 61
	v_readlane_b32 s35, v243, 3
	s_add_i32 s0, s23, s49
	v_and_b32_e32 v172, 15, v150
	v_or_b32_e32 v172, s54, v172
	v_or_b32_e32 v172, s24, v172
	v_lshrrev_b32_e32 v173, 2, v150
	v_and_b32_e32 v174, -4, v173
	v_add_u32_e32 v174, s0, v174
	v_and_b32_e32 v173, -8, v173
	v_and_b32_e32 v175, 16, v150
	v_add3_u32 v173, v173, v175, s0
	v_lshlrev_b32_e32 v175, 12, v172
	v_lshl_add_u32 v134, v174, 1, v175
	v_add_u32_e32 v135, 0x10000, v134
	v_add_u32_e32 v136, 0x80000, v134
	v_add_u32_e32 v137, 0x90000, v134
	v_lshlrev_b32_e32 v175, 12, v172
	v_lshl_add_u32 v138, v173, 1, v175
	v_add_u32_e32 v139, 0x10000, v138
	v_add_u32_e32 v140, 0x80000, v138
	v_add_u32_e32 v141, 0x90000, v138
	global_load_dwordx2 v[210:211], v134, s[26:27] offset:0
	global_load_dwordx2 v[212:213], v134, s[26:27] offset:32
	global_load_dwordx2 v[214:215], v134, s[26:27] offset:64
	global_load_dwordx2 v[216:217], v134, s[26:27] offset:96
	global_load_dwordx2 v[218:219], v135, s[26:27] offset:0
	global_load_dwordx2 v[220:221], v135, s[26:27] offset:32
	global_load_dwordx2 v[222:223], v135, s[26:27] offset:64
	global_load_dwordx2 v[224:225], v135, s[26:27] offset:96
	global_load_dwordx2 v[226:227], v136, s[26:27] offset:0
	global_load_dwordx2 v[228:229], v136, s[26:27] offset:32
	global_load_dwordx2 v[230:231], v136, s[26:27] offset:64
	global_load_dwordx2 v[232:233], v136, s[26:27] offset:96
	global_load_dwordx2 v[234:235], v137, s[26:27] offset:0
	global_load_dwordx2 v[236:237], v137, s[26:27] offset:32
	global_load_dwordx2 v[238:239], v137, s[26:27] offset:64
	global_load_dwordx2 v[240:241], v137, s[26:27] offset:96
	s_waitcnt vmcnt(15)
	v_lshlrev_b32_e32 v168, 16, v210
	v_and_b32_e32 v169, 0xffff0000, v210
	v_lshlrev_b32_e32 v170, 16, v211
	v_and_b32_e32 v171, 0xffff0000, v211
	v_pk_add_f32 v[124:125], v[124:125], v[168:169]
	v_pk_add_f32 v[126:127], v[126:127], v[170:171]
	global_load_dwordx2 v[210:211], v134, s[26:27] offset:256
	s_waitcnt vmcnt(15)
	v_lshlrev_b32_e32 v168, 16, v212
	v_and_b32_e32 v169, 0xffff0000, v212
	v_lshlrev_b32_e32 v170, 16, v213
	v_and_b32_e32 v171, 0xffff0000, v213
	v_pk_add_f32 v[116:117], v[116:117], v[168:169]
	v_pk_add_f32 v[118:119], v[118:119], v[170:171]
	global_load_dwordx2 v[212:213], v134, s[26:27] offset:288
	s_waitcnt vmcnt(15)
; __device__ __forceinline__ float bflo(unsigned u) { return __uint_as_float(u << 16); }
; __device__ __forceinline__ float bfhi(unsigned u) { return __uint_as_float(u & 0xffff0000u); }
; #define WIDE_STORE(BASE, LD, COFF, O) do { if ((m & 1) == 0) opend[n] = (O); \
;                 else *(uint4*)((BASE) + (size_t)tok * (LD) + (ncw - (COFF))) = swap_pair(opend[n], (O)); } while (0)
;     ...
;               const int nc = brow + ai * 128 + wr * 64 + m * 16 + fq * 4;
;               const int tok = bcol + bj * 128 + wc * 32 + n * 16 + fr;
;               const int ncw = brow + ai * 128 + wr * 64 + ((m & ~1) + (fq & 1)) * 16 + (fq & ~1) * 4;
;     ...
;               } else {
;                 uint2* ph = (uint2*)((u16*)(ws + OFF_RB) + (size_t)tok * DM + nc);
;                 const uint2 hb = *ph;
;                 uint2 o; o.x = pk2(bflo(hb.x) + v[0], bfhi(hb.x) + v[1]); o.y = pk2(bflo(hb.y) + v[2], bfhi(hb.y) + v[3]);
;                 WIDE_STORE((u16*)(ws + OFF_RB), DM, 0, o);
	v_lshlrev_b32_e32 v168, 16, v214
	v_and_b32_e32 v169, 0xffff0000, v214
	v_lshlrev_b32_e32 v170, 16, v215
	v_and_b32_e32 v171, 0xffff0000, v215
	v_pk_add_f32 v[108:109], v[108:109], v[168:169]
	v_pk_add_f32 v[110:111], v[110:111], v[170:171]
	global_load_dwordx2 v[214:215], v134, s[26:27] offset:320
	s_waitcnt vmcnt(15)
	v_lshlrev_b32_e32 v168, 16, v216
	v_and_b32_e32 v169, 0xffff0000, v216
	v_lshlrev_b32_e32 v170, 16, v217
	v_and_b32_e32 v171, 0xffff0000, v217
	v_pk_add_f32 v[100:101], v[100:101], v[168:169]
	v_pk_add_f32 v[102:103], v[102:103], v[170:171]
	global_load_dwordx2 v[216:217], v134, s[26:27] offset:352
	s_nop 0
	v_cvt_pk_bf16_f32 v124, v124, v125
	v_cvt_pk_bf16_f32 v125, v126, v127
	v_cvt_pk_bf16_f32 v126, v116, v117
	v_cvt_pk_bf16_f32 v127, v118, v119
	v_cvt_pk_bf16_f32 v108, v108, v109
	v_cvt_pk_bf16_f32 v109, v110, v111
	v_cvt_pk_bf16_f32 v110, v100, v101
	v_cvt_pk_bf16_f32 v111, v102, v103
	s_nop 1
	v_permlane16_swap_b32_e32 v124, v126
	v_permlane16_swap_b32_e32 v125, v127
	v_permlane16_swap_b32_e32 v108, v110
	v_permlane16_swap_b32_e32 v109, v111
	global_store_dwordx4 v138, v[124:127], s[26:27] offset:0
	global_store_dwordx4 v138, v[108:111], s[26:27] offset:64
	s_waitcnt vmcnt(17)
	v_lshlrev_b32_e32 v168, 16, v218
	v_and_b32_e32 v169, 0xffff0000, v218
	v_lshlrev_b32_e32 v170, 16, v219
	v_and_b32_e32 v171, 0xffff0000, v219
	v_pk_add_f32 v[120:121], v[120:121], v[168:169]
	v_pk_add_f32 v[122:123], v[122:123], v[170:171]
	global_load_dwordx2 v[218:219], v135, s[26:27] offset:256
	s_waitcnt vmcnt(17)
	v_lshlrev_b32_e32 v168, 16, v220
	v_and_b32_e32 v169, 0xffff0000, v220
	v_lshlrev_b32_e32 v170, 16, v221
	v_and_b32_e32 v171, 0xffff0000, v221
	v_pk_add_f32 v[112:113], v[112:113], v[168:169]
	v_pk_add_f32 v[114:115], v[114:115], v[170:171]
	global_load_dwordx2 v[220:221], v135, s[26:27] offset:288
	s_waitcnt vmcnt(17)
	v_lshlrev_b32_e32 v168, 16, v222
	v_and_b32_e32 v169, 0xffff0000, v222
	v_lshlrev_b32_e32 v170, 16, v223
	v_and_b32_e32 v171, 0xffff0000, v223
	v_pk_add_f32 v[104:105], v[104:105], v[168:169]
	v_pk_add_f32 v[106:107], v[106:107], v[170:171]
	global_load_dwordx2 v[222:223], v135, s[26:27] offset:320
	s_waitcnt vmcnt(17)
	v_lshlrev_b32_e32 v168, 16, v224
	v_and_b32_e32 v169, 0xffff0000, v224
	v_lshlrev_b32_e32 v170, 16, v225
	v_and_b32_e32 v171, 0xffff0000, v225
	v_pk_add_f32 v[96:97], v[96:97], v[168:169]
	v_pk_add_f32 v[98:99], v[98:99], v[170:171]
	global_load_dwordx2 v[224:225], v135, s[26:27] offset:352
	s_nop 0
	v_cvt_pk_bf16_f32 v120, v120, v121
	v_cvt_pk_bf16_f32 v121, v122, v123
	v_cvt_pk_bf16_f32 v122, v112, v113
	v_cvt_pk_bf16_f32 v123, v114, v115
	v_cvt_pk_bf16_f32 v104, v104, v105
	v_cvt_pk_bf16_f32 v105, v106, v107
	v_cvt_pk_bf16_f32 v106, v96, v97
	v_cvt_pk_bf16_f32 v107, v98, v99
	s_nop 1
	v_permlane16_swap_b32_e32 v120, v122
	v_permlane16_swap_b32_e32 v121, v123
	v_permlane16_swap_b32_e32 v104, v106
	v_permlane16_swap_b32_e32 v105, v107
	global_store_dwordx4 v139, v[120:123], s[26:27] offset:0
	global_store_dwordx4 v139, v[104:107], s[26:27] offset:64
	s_waitcnt vmcnt(19)
	v_lshlrev_b32_e32 v168, 16, v226
	v_and_b32_e32 v169, 0xffff0000, v226
	v_lshlrev_b32_e32 v170, 16, v227
	v_and_b32_e32 v171, 0xffff0000, v227
	v_pk_add_f32 v[92:93], v[92:93], v[168:169]
	v_pk_add_f32 v[94:95], v[94:95], v[170:171]
	global_load_dwordx2 v[226:227], v136, s[26:27] offset:256
	s_waitcnt vmcnt(19)
	v_lshlrev_b32_e32 v168, 16, v228
	v_and_b32_e32 v169, 0xffff0000, v228
	v_lshlrev_b32_e32 v170, 16, v229
	v_and_b32_e32 v171, 0xffff0000, v229
	v_pk_add_f32 v[84:85], v[84:85], v[168:169]
	v_pk_add_f32 v[86:87], v[86:87], v[170:171]
	global_load_dwordx2 v[228:229], v136, s[26:27] offset:288
	s_waitcnt vmcnt(19)
	v_lshlrev_b32_e32 v168, 16, v230
	v_and_b32_e32 v169, 0xffff0000, v230
	v_lshlrev_b32_e32 v170, 16, v231
	v_and_b32_e32 v171, 0xffff0000, v231
	v_pk_add_f32 v[76:77], v[76:77], v[168:169]
	v_pk_add_f32 v[78:79], v[78:79], v[170:171]
	global_load_dwordx2 v[230:231], v136, s[26:27] offset:320
	s_waitcnt vmcnt(19)
	v_lshlrev_b32_e32 v168, 16, v232
	v_and_b32_e32 v169, 0xffff0000, v232
	v_lshlrev_b32_e32 v170, 16, v233
	v_and_b32_e32 v171, 0xffff0000, v233
	v_pk_add_f32 v[68:69], v[68:69], v[168:169]
	v_pk_add_f32 v[70:71], v[70:71], v[170:171]
	global_load_dwordx2 v[232:233], v136, s[26:27] offset:352
	s_nop 0
	v_cvt_pk_bf16_f32 v92, v92, v93
	v_cvt_pk_bf16_f32 v93, v94, v95
	v_cvt_pk_bf16_f32 v94, v84, v85
	v_cvt_pk_bf16_f32 v95, v86, v87
	v_cvt_pk_bf16_f32 v76, v76, v77
	v_cvt_pk_bf16_f32 v77, v78, v79
	v_cvt_pk_bf16_f32 v78, v68, v69
	v_cvt_pk_bf16_f32 v79, v70, v71
	s_nop 1
	v_permlane16_swap_b32_e32 v92, v94
	v_permlane16_swap_b32_e32 v93, v95
	v_permlane16_swap_b32_e32 v76, v78
	v_permlane16_swap_b32_e32 v77, v79
	global_store_dwordx4 v140, v[92:95], s[26:27] offset:0
	global_store_dwordx4 v140, v[76:79], s[26:27] offset:64
	s_waitcnt vmcnt(21)
	v_lshlrev_b32_e32 v168, 16, v234
	v_and_b32_e32 v169, 0xffff0000, v234
	v_lshlrev_b32_e32 v170, 16, v235
	v_and_b32_e32 v171, 0xffff0000, v235
	v_pk_add_f32 v[88:89], v[88:89], v[168:169]
	v_pk_add_f32 v[90:91], v[90:91], v[170:171]
	global_load_dwordx2 v[234:235], v137, s[26:27] offset:256
	s_waitcnt vmcnt(21)
	v_lshlrev_b32_e32 v168, 16, v236
	v_and_b32_e32 v169, 0xffff0000, v236
	v_lshlrev_b32_e32 v170, 16, v237
	v_and_b32_e32 v171, 0xffff0000, v237
	v_pk_add_f32 v[80:81], v[80:81], v[168:169]
	v_pk_add_f32 v[82:83], v[82:83], v[170:171]
	global_load_dwordx2 v[236:237], v137, s[26:27] offset:288
	s_waitcnt vmcnt(21)
; __device__ __forceinline__ float bflo(unsigned u) { return __uint_as_float(u << 16); }
; __device__ __forceinline__ float bfhi(unsigned u) { return __uint_as_float(u & 0xffff0000u); }
; #define WIDE_STORE(BASE, LD, COFF, O) do { if ((m & 1) == 0) opend[n] = (O); \
;                 else *(uint4*)((BASE) + (size_t)tok * (LD) + (ncw - (COFF))) = swap_pair(opend[n], (O)); } while (0)
;     ...
;               const int nc = brow + ai * 128 + wr * 64 + m * 16 + fq * 4;
;               const int tok = bcol + bj * 128 + wc * 32 + n * 16 + fr;
;               const int ncw = brow + ai * 128 + wr * 64 + ((m & ~1) + (fq & 1)) * 16 + (fq & ~1) * 4;
;     ...
;               } else {
;                 uint2* ph = (uint2*)((u16*)(ws + OFF_RB) + (size_t)tok * DM + nc);
;                 const uint2 hb = *ph;
;                 uint2 o; o.x = pk2(bflo(hb.x) + v[0], bfhi(hb.x) + v[1]); o.y = pk2(bflo(hb.y) + v[2], bfhi(hb.y) + v[3]);
;                 WIDE_STORE((u16*)(ws + OFF_RB), DM, 0, o);
	v_lshlrev_b32_e32 v168, 16, v238
	v_and_b32_e32 v169, 0xffff0000, v238
	v_lshlrev_b32_e32 v170, 16, v239
	v_and_b32_e32 v171, 0xffff0000, v239
	v_pk_add_f32 v[72:73], v[72:73], v[168:169]
	v_pk_add_f32 v[74:75], v[74:75], v[170:171]
	global_load_dwordx2 v[238:239], v137, s[26:27] offset:320
	s_waitcnt vmcnt(21)
	v_lshlrev_b32_e32 v168, 16, v240
	v_and_b32_e32 v169, 0xffff0000, v240
	v_lshlrev_b32_e32 v170, 16, v241
	v_and_b32_e32 v171, 0xffff0000, v241
	v_pk_add_f32 v[64:65], v[64:65], v[168:169]
	v_pk_add_f32 v[66:67], v[66:67], v[170:171]
	global_load_dwordx2 v[240:241], v137, s[26:27] offset:352
	s_nop 0
	v_cvt_pk_bf16_f32 v88, v88, v89
	v_cvt_pk_bf16_f32 v89, v90, v91
	v_cvt_pk_bf16_f32 v90, v80, v81
	v_cvt_pk_bf16_f32 v91, v82, v83
	v_cvt_pk_bf16_f32 v72, v72, v73
	v_cvt_pk_bf16_f32 v73, v74, v75
	v_cvt_pk_bf16_f32 v74, v64, v65
	v_cvt_pk_bf16_f32 v75, v66, v67
	s_nop 1
	v_permlane16_swap_b32_e32 v88, v90
	v_permlane16_swap_b32_e32 v89, v91
	v_permlane16_swap_b32_e32 v72, v74
	v_permlane16_swap_b32_e32 v73, v75
	global_store_dwordx4 v141, v[88:91], s[26:27] offset:0
	global_store_dwordx4 v141, v[72:75], s[26:27] offset:64
	s_waitcnt vmcnt(23)
	v_lshlrev_b32_e32 v168, 16, v210
	v_and_b32_e32 v169, 0xffff0000, v210
	v_lshlrev_b32_e32 v170, 16, v211
	v_and_b32_e32 v171, 0xffff0000, v211
	v_pk_add_f32 v[60:61], v[60:61], v[168:169]
	v_pk_add_f32 v[62:63], v[62:63], v[170:171]
	s_waitcnt vmcnt(22)
	v_lshlrev_b32_e32 v168, 16, v212
	v_and_b32_e32 v169, 0xffff0000, v212
	v_lshlrev_b32_e32 v170, 16, v213
	v_and_b32_e32 v171, 0xffff0000, v213
	v_pk_add_f32 v[52:53], v[52:53], v[168:169]
	v_pk_add_f32 v[54:55], v[54:55], v[170:171]
	s_waitcnt vmcnt(21)
	v_lshlrev_b32_e32 v168, 16, v214
	v_and_b32_e32 v169, 0xffff0000, v214
	v_lshlrev_b32_e32 v170, 16, v215
	v_and_b32_e32 v171, 0xffff0000, v215
	v_pk_add_f32 v[44:45], v[44:45], v[168:169]
	v_pk_add_f32 v[46:47], v[46:47], v[170:171]
	s_waitcnt vmcnt(20)
	v_lshlrev_b32_e32 v168, 16, v216
	v_and_b32_e32 v169, 0xffff0000, v216
	v_lshlrev_b32_e32 v170, 16, v217
	v_and_b32_e32 v171, 0xffff0000, v217
	v_pk_add_f32 v[36:37], v[36:37], v[168:169]
	v_pk_add_f32 v[38:39], v[38:39], v[170:171]
	s_nop 0
	v_cvt_pk_bf16_f32 v60, v60, v61
	v_cvt_pk_bf16_f32 v61, v62, v63
	v_cvt_pk_bf16_f32 v62, v52, v53
	v_cvt_pk_bf16_f32 v63, v54, v55
	v_cvt_pk_bf16_f32 v44, v44, v45
	v_cvt_pk_bf16_f32 v45, v46, v47
	v_cvt_pk_bf16_f32 v46, v36, v37
	v_cvt_pk_bf16_f32 v47, v38, v39
	s_nop 1
	v_permlane16_swap_b32_e32 v60, v62
	v_permlane16_swap_b32_e32 v61, v63
	v_permlane16_swap_b32_e32 v44, v46
	v_permlane16_swap_b32_e32 v45, v47
	global_store_dwordx4 v138, v[60:63], s[26:27] offset:256
	global_store_dwordx4 v138, v[44:47], s[26:27] offset:320
	s_waitcnt vmcnt(19)
	v_lshlrev_b32_e32 v168, 16, v218
	v_and_b32_e32 v169, 0xffff0000, v218
	v_lshlrev_b32_e32 v170, 16, v219
	v_and_b32_e32 v171, 0xffff0000, v219
	v_pk_add_f32 v[56:57], v[56:57], v[168:169]
	v_pk_add_f32 v[58:59], v[58:59], v[170:171]
	s_waitcnt vmcnt(18)
	v_lshlrev_b32_e32 v168, 16, v220
	v_and_b32_e32 v169, 0xffff0000, v220
	v_lshlrev_b32_e32 v170, 16, v221
	v_and_b32_e32 v171, 0xffff0000, v221
	v_pk_add_f32 v[48:49], v[48:49], v[168:169]
	v_pk_add_f32 v[50:51], v[50:51], v[170:171]
	s_waitcnt vmcnt(17)
	v_lshlrev_b32_e32 v168, 16, v222
	v_and_b32_e32 v169, 0xffff0000, v222
	v_lshlrev_b32_e32 v170, 16, v223
	v_and_b32_e32 v171, 0xffff0000, v223
	v_pk_add_f32 v[40:41], v[40:41], v[168:169]
	v_pk_add_f32 v[42:43], v[42:43], v[170:171]
	s_waitcnt vmcnt(16)
	v_lshlrev_b32_e32 v168, 16, v224
	v_and_b32_e32 v169, 0xffff0000, v224
	v_lshlrev_b32_e32 v170, 16, v225
	v_and_b32_e32 v171, 0xffff0000, v225
	v_pk_add_f32 v[32:33], v[32:33], v[168:169]
	v_pk_add_f32 v[34:35], v[34:35], v[170:171]
	s_nop 0
	v_cvt_pk_bf16_f32 v56, v56, v57
	v_cvt_pk_bf16_f32 v57, v58, v59
	v_cvt_pk_bf16_f32 v58, v48, v49
	v_cvt_pk_bf16_f32 v59, v50, v51
	v_cvt_pk_bf16_f32 v40, v40, v41
	v_cvt_pk_bf16_f32 v41, v42, v43
	v_cvt_pk_bf16_f32 v42, v32, v33
	v_cvt_pk_bf16_f32 v43, v34, v35
	s_nop 1
	v_permlane16_swap_b32_e32 v56, v58
	v_permlane16_swap_b32_e32 v57, v59
	v_permlane16_swap_b32_e32 v40, v42
	v_permlane16_swap_b32_e32 v41, v43
	global_store_dwordx4 v139, v[56:59], s[26:27] offset:256
	global_store_dwordx4 v139, v[40:43], s[26:27] offset:320
	s_waitcnt vmcnt(15)
	v_lshlrev_b32_e32 v168, 16, v226
	v_and_b32_e32 v169, 0xffff0000, v226
	v_lshlrev_b32_e32 v170, 16, v227
	v_and_b32_e32 v171, 0xffff0000, v227
	v_pk_add_f32 v[28:29], v[28:29], v[168:169]
	v_pk_add_f32 v[30:31], v[30:31], v[170:171]
	s_waitcnt vmcnt(14)
	v_lshlrev_b32_e32 v168, 16, v228
	v_and_b32_e32 v169, 0xffff0000, v228
	v_lshlrev_b32_e32 v170, 16, v229
	v_and_b32_e32 v171, 0xffff0000, v229
	v_pk_add_f32 v[20:21], v[20:21], v[168:169]
	v_pk_add_f32 v[22:23], v[22:23], v[170:171]
	s_waitcnt vmcnt(13)
	v_lshlrev_b32_e32 v168, 16, v230
	v_and_b32_e32 v169, 0xffff0000, v230
	v_lshlrev_b32_e32 v170, 16, v231
	v_and_b32_e32 v171, 0xffff0000, v231
	v_pk_add_f32 v[12:13], v[12:13], v[168:169]
	v_pk_add_f32 v[14:15], v[14:15], v[170:171]
	s_waitcnt vmcnt(12)
	v_lshlrev_b32_e32 v168, 16, v232
	v_and_b32_e32 v169, 0xffff0000, v232
	v_lshlrev_b32_e32 v170, 16, v233
	v_and_b32_e32 v171, 0xffff0000, v233
	v_pk_add_f32 v[4:5], v[4:5], v[168:169]
	v_pk_add_f32 v[6:7], v[6:7], v[170:171]
	s_nop 0
	v_cvt_pk_bf16_f32 v28, v28, v29
	v_cvt_pk_bf16_f32 v29, v30, v31
	v_cvt_pk_bf16_f32 v30, v20, v21
	v_cvt_pk_bf16_f32 v31, v22, v23
	v_cvt_pk_bf16_f32 v12, v12, v13
	v_cvt_pk_bf16_f32 v13, v14, v15
	v_cvt_pk_bf16_f32 v14, v4, v5
	v_cvt_pk_bf16_f32 v15, v6, v7
	s_nop 1
	v_permlane16_swap_b32_e32 v28, v30
	v_permlane16_swap_b32_e32 v29, v31
	v_permlane16_swap_b32_e32 v12, v14
	v_permlane16_swap_b32_e32 v13, v15
	global_store_dwordx4 v140, v[28:31], s[26:27] offset:256
	global_store_dwordx4 v140, v[12:15], s[26:27] offset:320
	s_waitcnt vmcnt(11)
; __device__ __forceinline__ float bflo(unsigned u) { return __uint_as_float(u << 16); }
; __device__ __forceinline__ float bfhi(unsigned u) { return __uint_as_float(u & 0xffff0000u); }
; #define WIDE_STORE(BASE, LD, COFF, O) do { if ((m & 1) == 0) opend[n] = (O); \
;                 else *(uint4*)((BASE) + (size_t)tok * (LD) + (ncw - (COFF))) = swap_pair(opend[n], (O)); } while (0)
;     ...
;   for (int u = vb; u < nunits; u += ustride) {
;     const int tm = u % nM, tn = u / nM + ((tn_skip >= 0 && u / nM >= tn_skip) ? 1 : 0);
;     const int brow = tn * 256, bcol = tm * 256;
;     const int un = u + ustride;
;     const bool has_next = un < nunits;
;     const int tn_n = un / nM + ((tn_skip >= 0 && un / nM >= tn_skip) ? 1 : 0);
;     const int brow_n = has_next ? tn_n * 256 : brow, bcol_n = has_next ? (un % nM) * 256 : bcol;
; #pragma unroll
;     for (int a = 0; a < 2; ++a)
; #pragma unroll
;       for (int b = 0; b < 2; ++b)
; #pragma unroll
;         for (int m = 0; m < 4; ++m)
; #pragma unroll
;           for (int n = 0; n < 2; ++n) acc[a][b][m][n] = f32x4{0.f, 0.f, 0.f, 0.f};
;     ...
;               } else {
;                 uint2* ph = (uint2*)((u16*)(ws + OFF_RB) + (size_t)tok * DM + nc);
;                 const uint2 hb = *ph;
;                 uint2 o; o.x = pk2(bflo(hb.x) + v[0], bfhi(hb.x) + v[1]); o.y = pk2(bflo(hb.y) + v[2], bfhi(hb.y) + v[3]);
;                 WIDE_STORE((u16*)(ws + OFF_RB), DM, 0, o);
	v_lshlrev_b32_e32 v168, 16, v234
	v_and_b32_e32 v169, 0xffff0000, v234
	v_lshlrev_b32_e32 v170, 16, v235
	v_and_b32_e32 v171, 0xffff0000, v235
	v_pk_add_f32 v[24:25], v[24:25], v[168:169]
	v_pk_add_f32 v[26:27], v[26:27], v[170:171]
	s_waitcnt vmcnt(10)
	v_lshlrev_b32_e32 v168, 16, v236
	v_and_b32_e32 v169, 0xffff0000, v236
	v_lshlrev_b32_e32 v170, 16, v237
	v_and_b32_e32 v171, 0xffff0000, v237
	v_pk_add_f32 v[16:17], v[16:17], v[168:169]
	v_pk_add_f32 v[18:19], v[18:19], v[170:171]
	s_waitcnt vmcnt(9)
	v_lshlrev_b32_e32 v168, 16, v238
	v_and_b32_e32 v169, 0xffff0000, v238
	v_lshlrev_b32_e32 v170, 16, v239
	v_and_b32_e32 v171, 0xffff0000, v239
	v_pk_add_f32 v[8:9], v[8:9], v[168:169]
	v_pk_add_f32 v[10:11], v[10:11], v[170:171]
	s_waitcnt vmcnt(8)
	v_lshlrev_b32_e32 v168, 16, v240
	v_and_b32_e32 v169, 0xffff0000, v240
	v_lshlrev_b32_e32 v170, 16, v241
	v_and_b32_e32 v171, 0xffff0000, v241
	v_pk_add_f32 v[0:1], v[0:1], v[168:169]
	v_pk_add_f32 v[2:3], v[2:3], v[170:171]
	s_nop 0
	v_cvt_pk_bf16_f32 v24, v24, v25
	v_cvt_pk_bf16_f32 v25, v26, v27
	v_cvt_pk_bf16_f32 v26, v16, v17
	v_cvt_pk_bf16_f32 v27, v18, v19
	v_cvt_pk_bf16_f32 v8, v8, v9
	v_cvt_pk_bf16_f32 v9, v10, v11
	v_cvt_pk_bf16_f32 v10, v0, v1
	v_cvt_pk_bf16_f32 v11, v2, v3
	s_nop 1
	v_permlane16_swap_b32_e32 v24, v26
	v_permlane16_swap_b32_e32 v25, v27
	v_permlane16_swap_b32_e32 v8, v10
	v_permlane16_swap_b32_e32 v9, v11
	global_store_dwordx4 v141, v[24:27], s[26:27] offset:256
	global_store_dwordx4 v141, v[8:11], s[26:27] offset:320
	s_nop 1
	v_mov_b32_e32 v0, 0
	v_mov_b32_e32 v1, v0
	v_mov_b32_e32 v2, v0
	v_mov_b32_e32 v3, v0
	v_mov_b32_e32 v4, v0
	v_mov_b32_e32 v5, v0
	v_mov_b32_e32 v6, v0
	v_mov_b32_e32 v7, v0
	v_mov_b32_e32 v8, v0
	v_mov_b32_e32 v9, v0
	v_mov_b32_e32 v10, v0
	v_mov_b32_e32 v11, v0
	v_mov_b32_e32 v12, v0
	v_mov_b32_e32 v13, v0
	v_mov_b32_e32 v14, v0
	v_mov_b32_e32 v15, v0
	v_mov_b32_e32 v16, v0
	v_mov_b32_e32 v17, v0
	v_mov_b32_e32 v18, v0
	v_mov_b32_e32 v19, v0
	v_mov_b32_e32 v20, v0
	v_mov_b32_e32 v21, v0
	v_mov_b32_e32 v22, v0
	v_mov_b32_e32 v23, v0
	v_mov_b32_e32 v24, v0
	v_mov_b32_e32 v25, v0
	v_mov_b32_e32 v26, v0
	v_mov_b32_e32 v27, v0
	v_mov_b32_e32 v28, v0
	v_mov_b32_e32 v29, v0
	v_mov_b32_e32 v30, v0
	v_mov_b32_e32 v31, v0
	v_mov_b32_e32 v32, v0
	v_mov_b32_e32 v33, v0
	v_mov_b32_e32 v34, v0
	v_mov_b32_e32 v35, v0
	v_mov_b32_e32 v36, v0
	v_mov_b32_e32 v37, v0
	v_mov_b32_e32 v38, v0
	v_mov_b32_e32 v39, v0
	v_mov_b32_e32 v40, v0
	v_mov_b32_e32 v41, v0
	v_mov_b32_e32 v42, v0
	v_mov_b32_e32 v43, v0
	v_mov_b32_e32 v44, v0
	v_mov_b32_e32 v45, v0
	v_mov_b32_e32 v46, v0
	v_mov_b32_e32 v47, v0
	v_mov_b32_e32 v48, v0
	v_mov_b32_e32 v49, v0
	v_mov_b32_e32 v50, v0
	v_mov_b32_e32 v51, v0
	v_mov_b32_e32 v52, v0
	v_mov_b32_e32 v53, v0
	v_mov_b32_e32 v54, v0
	v_mov_b32_e32 v55, v0
	v_mov_b32_e32 v56, v0
	v_mov_b32_e32 v57, v0
	v_mov_b32_e32 v58, v0
	v_mov_b32_e32 v59, v0
	v_mov_b32_e32 v60, v0
	v_mov_b32_e32 v61, v0
	v_mov_b32_e32 v62, v0
	v_mov_b32_e32 v63, v0
	v_mov_b32_e32 v64, v0
	v_mov_b32_e32 v65, v0
	v_mov_b32_e32 v66, v0
	v_mov_b32_e32 v67, v0
	v_mov_b32_e32 v68, v0
	v_mov_b32_e32 v69, v0
	v_mov_b32_e32 v70, v0
	v_mov_b32_e32 v71, v0
	v_mov_b32_e32 v72, v0
	v_mov_b32_e32 v73, v0
	v_mov_b32_e32 v74, v0
	v_mov_b32_e32 v75, v0
	v_mov_b32_e32 v76, v0
	v_mov_b32_e32 v77, v0
	v_mov_b32_e32 v78, v0
	v_mov_b32_e32 v79, v0
	v_mov_b32_e32 v80, v0
	v_mov_b32_e32 v81, v0
	v_mov_b32_e32 v82, v0
	v_mov_b32_e32 v83, v0
	v_mov_b32_e32 v84, v0
	v_mov_b32_e32 v85, v0
	v_mov_b32_e32 v86, v0
	v_mov_b32_e32 v87, v0
	v_mov_b32_e32 v88, v0
	v_mov_b32_e32 v89, v0
	v_mov_b32_e32 v90, v0
	v_mov_b32_e32 v91, v0
	v_mov_b32_e32 v92, v0
	v_mov_b32_e32 v93, v0
	v_mov_b32_e32 v94, v0
	v_mov_b32_e32 v95, v0
	v_mov_b32_e32 v96, v0
	v_mov_b32_e32 v97, v0
	v_mov_b32_e32 v98, v0
	v_mov_b32_e32 v99, v0
	v_mov_b32_e32 v100, v0
	v_mov_b32_e32 v101, v0
	v_mov_b32_e32 v102, v0
	v_mov_b32_e32 v103, v0
	v_mov_b32_e32 v104, v0
	v_mov_b32_e32 v105, v0
	v_mov_b32_e32 v106, v0
	v_mov_b32_e32 v107, v0
	v_mov_b32_e32 v108, v0
	v_mov_b32_e32 v109, v0
	v_mov_b32_e32 v110, v0
	v_mov_b32_e32 v111, v0
	v_mov_b32_e32 v112, v0
	v_mov_b32_e32 v113, v0
	v_mov_b32_e32 v114, v0
	v_mov_b32_e32 v115, v0
	v_mov_b32_e32 v116, v0
	v_mov_b32_e32 v117, v0
	v_mov_b32_e32 v118, v0
	v_mov_b32_e32 v119, v0
	v_mov_b32_e32 v120, v0
	v_mov_b32_e32 v121, v0
	v_mov_b32_e32 v122, v0
	v_mov_b32_e32 v123, v0
	v_mov_b32_e32 v124, v0
	v_mov_b32_e32 v125, v0
	v_mov_b32_e32 v126, v0
	v_mov_b32_e32 v127, v0
	s_and_b64 s[98:99], s[56:57], s[8:9]
	s_andn2_b64 vcc, exec, s[6:7]
	s_mov_b32 s18, s22
	s_cbranch_vccz .Lhm1077_x
	s_ashr_i32 s0, s18, 31
	s_lshr_b32 s0, s0, 26
	s_add_i32 s0, s18, s0
	s_ashr_i32 s0, s0, 6
	v_readlane_b32 s6, v244, 20
	s_lshl_b32 s23, s0, 8
	s_add_i32 s22, s18, s6
	s_cmpk_lt_i32 s22, 0x200
	v_readlane_b32 s7, v244, 21
	s_cselect_b64 s[8:9], -1, 0
	s_cmpk_gt_i32 s22, 0x1ff
	s_cselect_b64 s[6:7], -1, 0
	s_and_b64 vcc, exec, s[6:7]
	s_mov_b32 s25, s23
	s_cbranch_vccnz .Lhm1077_0
	s_ashr_i32 s1, s22, 31
	s_lshr_b32 s1, s1, 26
	s_add_i32 s1, s22, s1
	s_lshl_b32 s1, s1, 2
	s_and_b32 s25, s1, 0xffffff00

;     ...
;   for (int u = vb; u < nunits; u += ustride) {
;     const int tm = u % nM, tn = u / nM + ((tn_skip >= 0 && u / nM >= tn_skip) ? 1 : 0);
;     const int brow = tn * 256, bcol = tm * 256;
;     const int un = u + ustride;
;     const bool has_next = un < nunits;
;     const int tn_n = un / nM + ((tn_skip >= 0 && un / nM >= tn_skip) ? 1 : 0);
;     const int brow_n = has_next ? tn_n * 256 : brow, bcol_n = has_next ? (un % nM) * 256 : bcol;
;     ...
;     asm volatile("s_waitcnt vmcnt(0)" ::: "memory");
;     if (has_next && wr == 1) __builtin_amdgcn_s_barrier();
.Lhm1077_1:
	s_or_b32 s27, s23, 0x80
	s_or_b32 s28, s26, 0x80
	s_or_b32 s29, s24, 0x80
	s_or_b32 s30, s25, 0x80
	v_mad_i64_i32 v[128:129], s[0:1], s23, v209, v[132:133]
	s_mov_b32 s31, 0
	s_mov_b64 s[40:41], 0xb0000
	s_waitcnt vmcnt(0)
	s_andn2_b64 vcc, exec, s[98:99]
	s_cbranch_vccnz .Lhm1077_k
	s_barrier
	s_branch .Lhm1077_k
